# stack: rescale-test chain trimmed in diff attention, queue-pop index prefetched one unit ahead, row-pass prefetch loads masked off on a wave's last row
# speedup vs baseline: 1.0102x; 1.0102x over previous
; __device__ __forceinline__ void xcd_barrier(const XcdBarrier& b) {
;     asm volatile("s_waitcnt vmcnt(0)" ::: "memory");
;     __syncthreads();
;     if (threadIdx.x == 0) {
;         unsigned* bar = b.bar;
;         __builtin_amdgcn_s_waitcnt(0);
; template <bool HAS_F, bool HAS_H, bool XIN_B = false, bool XOUT_B = false> ...
;     ...
;     for (int row = row_lo; row < row_lo + RPW; ++row) {
;         f32x4 x[4]; u32x2 fwv[4];
; #pragma unroll
;         for (int j = 0; j < 4; ++j) { x[j] = xn[j]; if (HAS_F) fwv[j] = fn[j]; }
;         { const int rn = (row + 1 < row_lo + RPW) ? row + 1 : row;
; #pragma unroll
;           for (int j = 0; j < 4; ++j) { RP_LDX(xn[j], rn, j); if (HAS_F) fn[j] = __builtin_nontemporal_load((const GAS u32x2*)(Fb + (size_t)rn * DM + 256 * j + 4 * lane)); } }
;         if (HAS_F) {
;             f32x4 f[4]; float ss = 0.f;
; #pragma unroll
;             for (int j = 0; j < 4; ++j) { const u32x2 fw = fwv[j];
;                 f[j] = (f32x4){__uint_as_float(fw.x << 16), __uint_as_float(fw.x & 0xffff0000u), __uint_as_float(fw.y << 16), __uint_as_float(fw.y & 0xffff0000u)}; ss += (f[j].x * f[j].x + f[j].y * f[j].y) + (f[j].z * f[j].z + f[j].w * f[j].w); }
;             const float rstd = 1.0f / sqrtf(wave_sum(ss) * (1.0f / DM) + RMS_EPS);
; #pragma unroll
;             for (int j = 0; j < 4; ++j) { x[j] = x[j] + f[j] * rstd * Cg[j];
;                 if (XOUT_B) { u32x2 w; w.x = pk_bf16(x[j].x, x[j].y); w.y = pk_bf16(x[j].z, x[j].w); *(GAS u32x2*)(xoutb + (size_t)row * DM + 256 * j + 4 * lane) = w;
;                     x[j] = (f32x4){__uint_as_float(w.x << 16), __uint_as_float(w.x & 0xffff0000u), __uint_as_float(w.y << 16), __uint_as_float(w.y & 0xffff0000u)}; }
;                 else __builtin_nontemporal_store(x[j], (GAS f32x4*)(xout + (size_t)row * DM + 256 * j + 4 * lane)); }
;         }
;         if (HAS_H) {
;             float ss = 0.f;
; #pragma unroll
;             for (int j = 0; j < 4; ++j) ss += (x[j].x * x[j].x + x[j].y * x[j].y) + (x[j].z * x[j].z + x[j].w * x[j].w);
;             const float rstd = 1.0f / sqrtf(wave_sum(ss) * (1.0f / DM) + RMS_EPS);
; #pragma unroll
;             for (int j = 0; j < 4; ++j) { const f32x4 h = x[j] * rstd * A[j] + Sh[j]; u32x2 w; w.x = pk_bf16(h.x, h.y); w.y = pk_bf16(h.z, h.w);
;                 *(GAS u32x2*)(H + (size_t)row * DM + 256 * j + 4 * lane) = w; }
.LBB0_91:
	s_add_i32 s7, s11, 1
	v_mul_f32_e32 v58, v17, v17
	v_mul_f32_e32 v59, v19, v19
	v_mul_f32_e32 v60, v21, v21
	v_mul_f32_e32 v61, v23, v23
	v_mul_f32_e32 v57, v57, v57
	v_mul_f32_e32 v56, v56, v56
	v_mul_f32_e32 v62, v29, v29
	v_mul_f32_e32 v63, v31, v31
	v_fmac_f32_e32 v58, v16, v16
	v_fmac_f32_e32 v59, v18, v18
	v_fmac_f32_e32 v60, v20, v20
	v_fmac_f32_e32 v61, v22, v22
	s_cmp_lt_i32 s11, s70
	v_fmac_f32_e32 v57, v54, v54
	v_fmac_f32_e32 v56, v55, v55
	v_fmac_f32_e32 v62, v28, v28
	v_fmac_f32_e32 v63, v30, v30
	v_add_f32_e32 v54, v58, v59
	v_add_f32_e32 v55, v60, v61
	s_cselect_b64 s[4:5], -1, 0
	v_add_f32_e32 v58, v62, v63
	s_and_b64 s[4:5], s[4:5], exec
	v_add_f32_e32 v54, v54, v55
	v_add_f32_e32 v56, v57, v56
	s_cselect_b32 s6, s7, s11
	v_add_f32_e32 v54, v58, v54
	s_mov_b32 s11, s7
	s_ashr_i32 s7, s6, 31
	v_add_f32_e32 v54, v56, v54
	s_lshl_b64 s[6:7], s[6:7], 12
	v_lshl_add_u64 v[70:71], v[32:33], 0, s[6:7]
	v_add_f32_dpp v54, v54, v54 quad_perm:[1,0,3,2] row_mask:0xf bank_mask:0xf bound_ctrl:1
	s_nop 1
	v_add_f32_dpp v58, v54, v54 quad_perm:[2,3,0,1] row_mask:0xf bank_mask:0xf bound_ctrl:1
	s_mov_b64 exec, s[4:5]
	global_load_dwordx4 v[54:57], v[70:71], off nt
	s_mov_b64 exec, -1
	s_nop 4
	s_nop 0
	v_add_f32_dpp v72, v58, v58 row_half_mirror row_mask:0xf bank_mask:0xf bound_ctrl:1
	s_mov_b64 exec, s[4:5]
	global_load_dwordx4 v[58:61], v[70:71], off offset:1024 nt
	global_load_dwordx4 v[62:65], v[70:71], off offset:2048 nt
	global_load_dwordx4 v[66:69], v[70:71], off offset:3072 nt
	s_mov_b64 exec, -1
	s_nop 4
	v_add_f32_dpp v70, v72, v72 row_mirror row_mask:0xf bank_mask:0xf bound_ctrl:1
	v_mov_b32_e32 v71, v70
	s_nop 1
	v_permlane16_swap_b32_e32 v70, v71
	v_add_f32_e32 v70, v70, v71
	v_mov_b32_e32 v71, v70
	s_nop 1
	v_permlane32_swap_b32_e32 v70, v71
	v_add_f32_e32 v70, v70, v71
	v_fmamk_f32 v70, v70, 0x3a800000, v52
	v_mul_f32_e32 v71, 0x4f800000, v70
	v_cmp_gt_f32_e32 vcc, s10, v70
	s_nop 1
	v_cndmask_b32_e32 v70, v70, v71, vcc
	v_sqrt_f32_e32 v71, v70
	s_nop 0
	v_add_u32_e32 v72, -1, v71
	v_add_u32_e32 v73, 1, v71
	v_fma_f32 v74, -v72, v71, v70
	v_fma_f32 v75, -v73, v71, v70
	v_cmp_ge_f32_e64 s[6:7], 0, v74
	s_nop 1
	v_cndmask_b32_e64 v71, v71, v72, s[6:7]
	v_cmp_lt_f32_e64 s[6:7], 0, v75
	s_nop 1
	v_cndmask_b32_e64 v71, v71, v73, s[6:7]
	v_mul_f32_e32 v72, 0x37800000, v71
	v_cndmask_b32_e32 v71, v71, v72, vcc
	v_cmp_class_f32_e32 vcc, v70, v53
	s_nop 1
	v_cndmask_b32_e32 v70, v71, v70, vcc
	v_div_scale_f32 v71, s[6:7], v70, v70, 1.0
	v_rcp_f32_e32 v73, v71
	v_div_scale_f32 v72, vcc, 1.0, v70, 1.0
	v_fma_f32 v74, -v71, v73, 1.0
	v_fmac_f32_e32 v73, v74, v73
	v_mul_f32_e32 v74, v72, v73
	v_fma_f32 v75, -v71, v74, v72
	v_fmac_f32_e32 v74, v75, v73
	v_fma_f32 v71, -v71, v74, v72
	v_div_fmas_f32 v71, v71, v73, v74
	v_div_fixup_f32 v70, v71, v70, 1.0
	v_pk_mul_f32 v[16:17], v[16:17], v[70:71] op_sel_hi:[1,0]
	v_pk_mul_f32 v[18:19], v[18:19], v[70:71] op_sel_hi:[1,0]
	v_pk_fma_f32 v[16:17], v[38:39], v[16:17], v[8:9]
	v_pk_mul_f32 v[20:21], v[20:21], v[70:71] op_sel_hi:[1,0]
	v_pk_mul_f32 v[22:23], v[22:23], v[70:71] op_sel_hi:[1,0]
	v_pk_fma_f32 v[18:19], v[36:37], v[18:19], v[10:11]
	v_cvt_pk_bf16_f32 v16, v16, v17
	v_pk_mul_f32 v[28:29], v[28:29], v[70:71] op_sel_hi:[1,0]
	v_cvt_pk_bf16_f32 v17, v18, v19
	v_pk_mul_f32 v[30:31], v[30:31], v[70:71] op_sel_hi:[1,0]
	v_pk_mul_f32 v[24:25], v[24:25], v[70:71] op_sel_hi:[1,0]
	v_pk_mul_f32 v[26:27], v[26:27], v[70:71] op_sel_hi:[1,0]
	v_pk_fma_f32 v[22:23], v[40:41], v[22:23], v[2:3]
	v_pk_fma_f32 v[20:21], v[42:43], v[20:21], v[0:1]
	global_store_dwordx2 v[34:35], v[16:17], off offset:-1536
	v_cvt_pk_bf16_f32 v16, v20, v21
	v_cvt_pk_bf16_f32 v17, v22, v23
	v_pk_fma_f32 v[30:31], v[44:45], v[30:31], v[6:7]
	v_pk_fma_f32 v[28:29], v[46:47], v[28:29], v[4:5]
	v_pk_fma_f32 v[26:27], v[48:49], v[26:27], v[14:15]
	v_pk_fma_f32 v[24:25], v[50:51], v[24:25], v[12:13]
	global_store_dwordx2 v[34:35], v[16:17], off offset:-1024
	v_cvt_pk_bf16_f32 v16, v28, v29
	v_cvt_pk_bf16_f32 v17, v30, v31
	global_store_dwordx2 v[34:35], v[16:17], off offset:-512
	v_cvt_pk_bf16_f32 v16, v24, v25
	v_cvt_pk_bf16_f32 v17, v26, v27
	global_store_dwordx2 v[34:35], v[16:17], off
	s_waitcnt vmcnt(4)
	v_mov_b64_e32 v[24:25], v[66:67]
	v_lshl_add_u64 v[34:35], v[34:35], 0, s[8:9]
	v_mov_b32_e32 v16, v54
	v_mov_b32_e32 v17, v55
	v_mov_b32_e32 v18, v56
	v_mov_b32_e32 v19, v57
	v_mov_b32_e32 v20, v58
	v_mov_b32_e32 v21, v59
	v_mov_b32_e32 v22, v60
	v_mov_b32_e32 v23, v61
	v_mov_b32_e32 v28, v62
	v_mov_b32_e32 v29, v63
	v_mov_b32_e32 v30, v64
	v_mov_b32_e32 v31, v65
	v_mov_b32_e32 v54, v66
	v_mov_b32_e32 v57, v67
	v_mov_b32_e32 v55, v68
	v_mov_b32_e32 v56, v69
	v_mov_b64_e32 v[26:27], v[68:69]
	s_mov_b64 vcc, s[4:5]
	s_cbranch_vccnz .LBB0_91
	s_waitcnt vmcnt(0)
	s_barrier
	s_and_saveexec_b64 s[4:5], s[26:27]
	s_xor_b64 s[38:39], exec, s[4:5]
	s_cbranch_execz .LBB0_137
	s_add_i32 s4, 0, 0x20020
	v_mov_b32_e32 v0, s4
	s_waitcnt vmcnt(0) expcnt(0) lgkmcnt(0)
	ds_read_b32 v2, v0
	s_add_i32 s4, 0, 0x20024
	v_mov_b32_e32 v0, s4
	ds_read_b32 v0, v0
	s_waitcnt lgkmcnt(1)
	v_cmp_ne_u32_e32 vcc, 0, v2
	s_cbranch_vccnz .LBB0_107
	s_add_u32 s4, s40, 0x80200
	s_addc_u32 s5, s41, 0
	s_add_u32 s8, s40, 0x80400
	s_addc_u32 s9, s41, 0
	s_add_u32 s10, s40, 0x80500
	s_addc_u32 s11, s41, 0
	s_add_u32 s12, s40, 0x80600
	s_addc_u32 s13, s41, 0
	s_add_u32 s14, s40, 0x80700
	s_addc_u32 s15, s41, 0
	s_add_u32 s16, s40, 0x80800
	s_addc_u32 s17, s41, 0
	s_add_u32 s18, s40, 0x80900
	s_addc_u32 s19, s41, 0
	s_add_u32 s20, s40, 0x80a00
	s_addc_u32 s21, s41, 0
	s_add_u32 s22, s40, 0x80b00
	s_addc_u32 s23, s41, 0
	s_add_u32 s28, s40, 0x80c00
	s_addc_u32 s29, s41, 0
	s_add_u32 s30, s40, 0x80d00
	s_addc_u32 s31, s41, 0
	s_add_u32 s34, s40, 0x80e00
	s_addc_u32 s35, s41, 0
	s_add_u32 s36, s40, 0x80f00
	s_addc_u32 s37, s41, 0
	s_add_u32 s48, s40, 0x81000
	s_addc_u32 s49, s41, 0
	s_add_u32 s50, s40, 0x81100
	s_addc_u32 s51, s41, 0
	s_add_u32 s54, s40, 0x81200
	s_addc_u32 s55, s41, 0
	s_add_u32 s56, s40, 0x81300
	s_mul_i32 s24, s43, s92
	s_addc_u32 s57, s41, 0
	s_mul_i32 s24, s24, s42
	s_mov_b32 s25, 1
	s_mov_b64 s[6:7], 0
	s_waitcnt lgkmcnt(0)
	v_mov_b64_e32 v[0:1], s[8:9]
	v_mov_b64_e32 v[2:3], s[10:11]
	v_mov_b64_e32 v[4:5], s[12:13]
	v_mov_b64_e32 v[6:7], s[14:15]
	v_mov_b64_e32 v[8:9], s[16:17]
	v_mov_b64_e32 v[10:11], s[18:19]
	v_mov_b64_e32 v[12:13], s[20:21]
	v_mov_b64_e32 v[14:15], s[22:23]
	v_mov_b64_e32 v[16:17], s[28:29]
	v_mov_b64_e32 v[18:19], s[30:31]
	v_mov_b64_e32 v[20:21], s[34:35]
	v_mov_b64_e32 v[22:23], s[36:37]
	v_mov_b64_e32 v[24:25], s[48:49]
	v_mov_b64_e32 v[26:27], s[50:51]
	v_mov_b64_e32 v[28:29], s[54:55]
	v_mov_b64_e32 v[30:31], s[56:57]
	s_branch .LBB0_97

; #define GAS __attribute__((address_space(1)))
; __device__ __forceinline__ float wave_sum(float v) { return xrow_sum(row16_sum(v)); }
; __device__ __forceinline__ unsigned pk_bf16(float lo, float hi) { return pg8::cvt_pk_bf16(lo, hi); }
; template <bool HAS_F, bool HAS_H, bool XIN_B = false, bool XOUT_B = false> ...
;     ...
;     for (int row = row_lo; row < row_lo + RPW; ++row) {
;         f32x4 x[4]; u32x2 fwv[4];
; #pragma unroll
;         for (int j = 0; j < 4; ++j) { x[j] = xn[j]; if (HAS_F) fwv[j] = fn[j]; }
;         { const int rn = (row + 1 < row_lo + RPW) ? row + 1 : row;
; #pragma unroll
;           for (int j = 0; j < 4; ++j) { RP_LDX(xn[j], rn, j); if (HAS_F) fn[j] = __builtin_nontemporal_load((const GAS u32x2*)(Fb + (size_t)rn * DM + 256 * j + 4 * lane)); } }
;         if (HAS_F) {
;             f32x4 f[4]; float ss = 0.f;
; #pragma unroll
;             for (int j = 0; j < 4; ++j) { const u32x2 fw = fwv[j];
;                 f[j] = (f32x4){__uint_as_float(fw.x << 16), __uint_as_float(fw.x & 0xffff0000u), __uint_as_float(fw.y << 16), __uint_as_float(fw.y & 0xffff0000u)}; ss += (f[j].x * f[j].x + f[j].y * f[j].y) + (f[j].z * f[j].z + f[j].w * f[j].w); }
;             const float rstd = 1.0f / sqrtf(wave_sum(ss) * (1.0f / DM) + RMS_EPS);
; #pragma unroll
;             for (int j = 0; j < 4; ++j) { x[j] = x[j] + f[j] * rstd * Cg[j];
;                 if (XOUT_B) { u32x2 w; w.x = pk_bf16(x[j].x, x[j].y); w.y = pk_bf16(x[j].z, x[j].w); *(GAS u32x2*)(xoutb + (size_t)row * DM + 256 * j + 4 * lane) = w;
;                     x[j] = (f32x4){__uint_as_float(w.x << 16), __uint_as_float(w.x & 0xffff0000u), __uint_as_float(w.y << 16), __uint_as_float(w.y & 0xffff0000u)}; }
;                 else __builtin_nontemporal_store(x[j], (GAS f32x4*)(xout + (size_t)row * DM + 256 * j + 4 * lane)); }
.LBB0_264:
	v_lshl_add_u64 v[86:87], s[10:11], 0, v[32:33]
	s_add_i32 s6, s15, 1
	v_lshlrev_b32_e32 v70, 16, v72
	v_and_b32_e32 v71, 0xffff0000, v72
	v_lshlrev_b32_e32 v72, 16, v73
	v_and_b32_e32 v73, 0xffff0000, v73
	v_lshlrev_b32_e32 v74, 16, v76
	v_and_b32_e32 v75, 0xffff0000, v76
	v_lshlrev_b32_e32 v76, 16, v77
	v_and_b32_e32 v77, 0xffff0000, v77
	v_add_co_u32_e32 v106, vcc, s13, v86
	v_lshlrev_b32_e32 v78, 16, v80
	v_and_b32_e32 v79, 0xffff0000, v80
	v_lshlrev_b32_e32 v80, 16, v81
	v_and_b32_e32 v81, 0xffff0000, v81
	v_lshl_add_u64 v[90:91], s[8:9], 0, v[32:33]
	s_cmp_lt_i32 s15, s70
	v_mul_f32_e32 v92, v71, v71
	v_mul_f32_e32 v93, v73, v73
	v_mul_f32_e32 v94, v75, v75
	v_mul_f32_e32 v95, v77, v77
	v_addc_co_u32_e32 v107, vcc, 0, v87, vcc
	v_lshlrev_b32_e32 v82, 16, v84
	v_and_b32_e32 v83, 0xffff0000, v84
	v_lshlrev_b32_e32 v84, 16, v85
	v_and_b32_e32 v85, 0xffff0000, v85
	v_mul_f32_e32 v96, v79, v79
	v_mul_f32_e32 v97, v81, v81
	v_add_co_u32_e32 v86, vcc, s14, v90
	s_cselect_b64 s[4:5], -1, 0
	v_fmac_f32_e32 v92, v70, v70
	v_fmac_f32_e32 v93, v72, v72
	v_fmac_f32_e32 v94, v74, v74
	v_fmac_f32_e32 v95, v76, v76
	v_mul_f32_e32 v98, v83, v83
	v_mul_f32_e32 v99, v85, v85
	v_addc_co_u32_e32 v87, vcc, 0, v91, vcc
	v_fmac_f32_e32 v96, v78, v78
	v_fmac_f32_e32 v97, v80, v80
	s_and_b64 s[4:5], s[4:5], exec
	v_add_f32_e32 v90, v92, v93
	v_add_f32_e32 v91, v94, v95
	v_fmac_f32_e32 v98, v82, v82
	v_fmac_f32_e32 v99, v84, v84
	v_add_f32_e32 v92, v96, v97
	s_cselect_b32 s16, s6, s15
	v_add_f32_e32 v90, v91, v90
	v_add_f32_e32 v93, v98, v99
	s_ashr_i32 s17, s16, 31
	v_add_f32_e32 v90, v92, v90
	s_mov_b32 s15, s6
	s_lshl_b64 s[6:7], s[16:17], 12
	v_add_f32_e32 v90, v93, v90
	s_lshl_b64 s[16:17], s[16:17], 11
	v_lshl_add_u64 v[108:109], v[34:35], 0, s[6:7]
	v_add_f32_dpp v120, v90, v90 quad_perm:[1,0,3,2] row_mask:0xf bank_mask:0xf bound_ctrl:1
	v_lshl_add_u64 v[110:111], v[68:69], 0, s[16:17]
	s_mov_b64 exec, s[4:5]
	global_load_dwordx4 v[90:93], v[108:109], off nt
	global_load_dwordx4 v[94:97], v[108:109], off offset:1024 nt
	global_load_dwordx4 v[98:101], v[108:109], off offset:2048 nt
	global_load_dwordx4 v[102:105], v[108:109], off offset:3072 nt
	global_load_dwordx2 v[112:113], v[110:111], off nt
	global_load_dwordx2 v[114:115], v[110:111], off offset:512 nt
	global_load_dwordx2 v[116:117], v[110:111], off offset:1024 nt
	global_load_dwordx2 v[118:119], v[110:111], off offset:1536 nt
	s_mov_b64 exec, -1
	s_nop 4
	v_add_f32_dpp v108, v120, v120 quad_perm:[2,3,0,1] row_mask:0xf bank_mask:0xf bound_ctrl:1
	s_add_u32 s8, s8, 0x800
	s_addc_u32 s9, s9, 0
	v_add_f32_dpp v108, v108, v108 row_half_mirror row_mask:0xf bank_mask:0xf bound_ctrl:1
	s_add_u32 s10, s10, 0x800
	s_addc_u32 s11, s11, 0
	v_add_f32_dpp v108, v108, v108 row_mirror row_mask:0xf bank_mask:0xf bound_ctrl:1
	v_mov_b32_e32 v109, v108
	s_nop 1
	v_permlane16_swap_b32_e32 v108, v109
	v_add_f32_e32 v108, v108, v109
	v_mov_b32_e32 v109, v108
	s_nop 1
	v_permlane32_swap_b32_e32 v108, v109
	v_add_f32_e32 v108, v108, v109
	v_fmamk_f32 v108, v108, 0x3a800000, v88
	v_mul_f32_e32 v109, 0x4f800000, v108
	v_cmp_gt_f32_e32 vcc, s12, v108
	s_nop 1
	v_cndmask_b32_e32 v108, v108, v109, vcc
	v_sqrt_f32_e32 v109, v108
	s_nop 0
	v_add_u32_e32 v110, -1, v109
	v_add_u32_e32 v111, 1, v109
	v_fma_f32 v120, -v110, v109, v108
	v_fma_f32 v121, -v111, v109, v108
	v_cmp_ge_f32_e64 s[6:7], 0, v120
	s_nop 1
	v_cndmask_b32_e64 v109, v109, v110, s[6:7]
	v_cmp_lt_f32_e64 s[6:7], 0, v121
	s_nop 1
	v_cndmask_b32_e64 v109, v109, v111, s[6:7]
	v_mul_f32_e32 v110, 0x37800000, v109
	v_cndmask_b32_e32 v109, v109, v110, vcc
	v_cmp_class_f32_e32 vcc, v108, v89
	s_nop 1
	v_cndmask_b32_e32 v108, v109, v108, vcc
	v_div_scale_f32 v109, s[6:7], v108, v108, 1.0
	v_rcp_f32_e32 v111, v109
	v_div_scale_f32 v110, vcc, 1.0, v108, 1.0
	v_fma_f32 v120, -v109, v111, 1.0
	v_fmac_f32_e32 v111, v120, v111
	v_mul_f32_e32 v120, v110, v111
	v_fma_f32 v121, -v109, v120, v110
	v_fmac_f32_e32 v120, v121, v111
	v_fma_f32 v109, -v109, v120, v110
	v_div_fmas_f32 v109, v109, v111, v120
	v_div_fixup_f32 v108, v109, v108, 1.0
	v_pk_mul_f32 v[70:71], v[70:71], v[108:109] op_sel_hi:[1,0]
	v_pk_mul_f32 v[72:73], v[72:73], v[108:109] op_sel_hi:[1,0]
	v_pk_fma_f32 v[16:17], v[38:39], v[70:71], v[16:17]
	v_pk_mul_f32 v[74:75], v[74:75], v[108:109] op_sel_hi:[1,0]
	v_pk_mul_f32 v[76:77], v[76:77], v[108:109] op_sel_hi:[1,0]
	v_pk_fma_f32 v[18:19], v[36:37], v[72:73], v[18:19]
	v_cvt_pk_bf16_f32 v16, v16, v17
	v_pk_mul_f32 v[78:79], v[78:79], v[108:109] op_sel_hi:[1,0]
	v_cvt_pk_bf16_f32 v17, v18, v19
	v_pk_mul_f32 v[80:81], v[80:81], v[108:109] op_sel_hi:[1,0]
	v_pk_mul_f32 v[82:83], v[82:83], v[108:109] op_sel_hi:[1,0]
	v_pk_fma_f32 v[22:23], v[40:41], v[76:77], v[22:23]
	v_pk_fma_f32 v[20:21], v[42:43], v[74:75], v[20:21]
	global_store_dwordx2 v[106:107], v[16:17], off
	v_lshlrev_b32_e32 v70, 16, v16
	v_and_b32_e32 v71, 0xffff0000, v16
	v_lshlrev_b32_e32 v74, 16, v17
	v_and_b32_e32 v75, 0xffff0000, v17
	v_cvt_pk_bf16_f32 v16, v20, v21
	v_cvt_pk_bf16_f32 v17, v22, v23
	v_pk_mul_f32 v[84:85], v[84:85], v[108:109] op_sel_hi:[1,0]
	v_pk_fma_f32 v[26:27], v[64:65], v[80:81], v[26:27]
	v_pk_fma_f32 v[24:25], v[66:67], v[78:79], v[24:25]
	v_pk_fma_f32 v[28:29], v[46:47], v[82:83], v[28:29]
	global_store_dwordx2 v[106:107], v[16:17], off offset:512
	v_lshlrev_b32_e32 v78, 16, v16
	v_and_b32_e32 v79, 0xffff0000, v16
	v_lshlrev_b32_e32 v82, 16, v17
	v_and_b32_e32 v83, 0xffff0000, v17
	v_cvt_pk_bf16_f32 v16, v24, v25
	v_cvt_pk_bf16_f32 v17, v26, v27
	v_mul_f32_e32 v18, v71, v71
	v_mul_f32_e32 v19, v75, v75
	v_pk_fma_f32 v[30:31], v[44:45], v[84:85], v[30:31]
	global_store_dwordx2 v[106:107], v[16:17], off offset:1024
	v_lshlrev_b32_e32 v108, 16, v16
	v_and_b32_e32 v109, 0xffff0000, v16
	v_lshlrev_b32_e32 v110, 16, v17
	v_and_b32_e32 v111, 0xffff0000, v17
	v_cvt_pk_bf16_f32 v16, v28, v29
	v_cvt_pk_bf16_f32 v17, v30, v31
	v_fmac_f32_e32 v18, v70, v70
	v_fmac_f32_e32 v19, v74, v74
	v_mul_f32_e32 v20, v79, v79
	v_mul_f32_e32 v21, v83, v83
	global_store_dwordx2 v[106:107], v[16:17], off offset:1536
	v_lshlrev_b32_e32 v106, 16, v16
	v_and_b32_e32 v107, 0xffff0000, v16
	v_lshlrev_b32_e32 v120, 16, v17
	v_and_b32_e32 v121, 0xffff0000, v17
	v_add_f32_e32 v16, v18, v19
	v_fmac_f32_e32 v20, v78, v78
	v_fmac_f32_e32 v21, v82, v82
	v_mul_f32_e32 v17, v109, v109
	v_mul_f32_e32 v18, v111, v111
	v_add_f32_e32 v19, v20, v21
	v_fmac_f32_e32 v17, v108, v108
	v_fmac_f32_e32 v18, v110, v110
	v_mul_f32_e32 v20, v107, v107
	v_mul_f32_e32 v21, v121, v121
	v_add_f32_e32 v16, v16, v19
	v_add_f32_e32 v17, v17, v18
	v_fmac_f32_e32 v20, v106, v106
	v_fmac_f32_e32 v21, v120, v120
	v_add_f32_e32 v16, v16, v17
	v_add_f32_e32 v17, v20, v21
	v_add_f32_e32 v16, v16, v17
	s_waitcnt vmcnt(9)
; #define GAS __attribute__((address_space(1)))
; __device__ __forceinline__ float wave_sum(float v) { return xrow_sum(row16_sum(v)); }
; __device__ __forceinline__ unsigned pk_bf16(float lo, float hi) { return pg8::cvt_pk_bf16(lo, hi); }
; __device__ __forceinline__ void xcd_barrier(const XcdBarrier& b) {
;     asm volatile("s_waitcnt vmcnt(0)" ::: "memory");
;     __syncthreads();
;     if (threadIdx.x == 0) {
;         unsigned* bar = b.bar;
;         __builtin_amdgcn_s_waitcnt(0);
;         unsigned nloc = b.st[0], nx = b.st[1];
;         if (nloc == 0u) { xcd_barrier_complete(bar, b.x, nloc, nx); b.st[0] = nloc; b.st[1] = nx; }
; template <bool HAS_F, bool HAS_H, bool XIN_B = false, bool XOUT_B = false> ...
;     ...
;         if (HAS_H) {
;             float ss = 0.f;
; #pragma unroll
;             for (int j = 0; j < 4; ++j) ss += (x[j].x * x[j].x + x[j].y * x[j].y) + (x[j].z * x[j].z + x[j].w * x[j].w);
;             const float rstd = 1.0f / sqrtf(wave_sum(ss) * (1.0f / DM) + RMS_EPS);
; #pragma unroll
;             for (int j = 0; j < 4; ++j) { const f32x4 h = x[j] * rstd * A[j] + Sh[j]; u32x2 w; w.x = pk_bf16(h.x, h.y); w.y = pk_bf16(h.z, h.w);
;                 *(GAS u32x2*)(H + (size_t)row * DM + 256 * j + 4 * lane) = w; }
	v_mov_b64_e32 v[24:25], v[98:99]
	s_waitcnt vmcnt(8)
	v_mov_b64_e32 v[28:29], v[102:103]
	v_add_f32_dpp v16, v16, v16 quad_perm:[1,0,3,2] row_mask:0xf bank_mask:0xf bound_ctrl:1
	s_waitcnt vmcnt(4)
	v_mov_b64_e32 v[84:85], v[118:119]
	v_mov_b64_e32 v[80:81], v[116:117]
	v_add_f32_dpp v16, v16, v16 quad_perm:[2,3,0,1] row_mask:0xf bank_mask:0xf bound_ctrl:1
	v_mov_b64_e32 v[76:77], v[114:115]
	v_mov_b64_e32 v[72:73], v[112:113]
	v_add_f32_dpp v16, v16, v16 row_half_mirror row_mask:0xf bank_mask:0xf bound_ctrl:1
	v_mov_b64_e32 v[26:27], v[100:101]
	v_mov_b64_e32 v[30:31], v[104:105]
	v_add_f32_dpp v16, v16, v16 row_mirror row_mask:0xf bank_mask:0xf bound_ctrl:1
	v_mov_b32_e32 v17, v16
	s_nop 1
	v_permlane16_swap_b32_e32 v16, v17
	v_add_f32_e32 v16, v16, v17
	v_mov_b32_e32 v17, v16
	s_nop 1
	v_permlane32_swap_b32_e32 v16, v17
	v_add_f32_e32 v16, v16, v17
	v_fmamk_f32 v16, v16, 0x3a800000, v88
	v_mul_f32_e32 v17, 0x4f800000, v16
	v_cmp_gt_f32_e32 vcc, s12, v16
	s_nop 1
	v_cndmask_b32_e32 v16, v16, v17, vcc
	v_sqrt_f32_e32 v17, v16
	s_nop 0
	v_add_u32_e32 v18, -1, v17
	v_add_u32_e32 v19, 1, v17
	v_fma_f32 v20, -v18, v17, v16
	v_fma_f32 v21, -v19, v17, v16
	v_cmp_ge_f32_e64 s[6:7], 0, v20
	s_nop 1
	v_cndmask_b32_e64 v17, v17, v18, s[6:7]
	v_cmp_lt_f32_e64 s[6:7], 0, v21
	v_mov_b64_e32 v[20:21], v[94:95]
	v_mov_b64_e32 v[22:23], v[96:97]
	v_cndmask_b32_e64 v17, v17, v19, s[6:7]
	v_mul_f32_e32 v18, 0x37800000, v17
	v_cndmask_b32_e32 v17, v17, v18, vcc
	v_cmp_class_f32_e32 vcc, v16, v89
	s_nop 1
	v_cndmask_b32_e32 v122, v17, v16, vcc
	v_div_scale_f32 v123, s[6:7], v122, v122, 1.0
	v_rcp_f32_e32 v125, v123
	v_div_scale_f32 v124, vcc, 1.0, v122, 1.0
	v_fma_f32 v16, -v123, v125, 1.0
	v_fmac_f32_e32 v125, v16, v125
	v_mul_f32_e32 v126, v124, v125
	v_fma_f32 v16, -v123, v126, v124
	v_fmac_f32_e32 v126, v16, v125
	v_mov_b64_e32 v[16:17], v[90:91]
	v_mov_b64_e32 v[18:19], v[92:93]
	v_fma_f32 v90, -v123, v126, v124
	v_div_fmas_f32 v90, v90, v125, v126
	v_div_fixup_f32 v90, v90, v122, 1.0
	v_pk_mul_f32 v[70:71], v[70:71], v[90:91] op_sel_hi:[1,0]
	v_pk_mul_f32 v[74:75], v[74:75], v[90:91] op_sel_hi:[1,0]
	v_pk_fma_f32 v[70:71], v[50:51], v[70:71], v[12:13]
	v_pk_mul_f32 v[78:79], v[78:79], v[90:91] op_sel_hi:[1,0]
	v_pk_mul_f32 v[82:83], v[82:83], v[90:91] op_sel_hi:[1,0]
	v_pk_fma_f32 v[74:75], v[48:49], v[74:75], v[14:15]
	v_cvt_pk_bf16_f32 v70, v70, v71
	v_pk_mul_f32 v[92:93], v[108:109], v[90:91] op_sel_hi:[1,0]
	v_cvt_pk_bf16_f32 v71, v74, v75
	v_pk_mul_f32 v[94:95], v[110:111], v[90:91] op_sel_hi:[1,0]
	v_pk_fma_f32 v[82:83], v[52:53], v[82:83], v[2:3]
	v_pk_fma_f32 v[78:79], v[54:55], v[78:79], v[0:1]
	global_store_dwordx2 v[86:87], v[70:71], off
	v_cvt_pk_bf16_f32 v70, v78, v79
	v_cvt_pk_bf16_f32 v71, v82, v83
	v_pk_mul_f32 v[96:97], v[106:107], v[90:91] op_sel_hi:[1,0]
	v_pk_mul_f32 v[90:91], v[120:121], v[90:91] op_sel_hi:[1,0]
	v_pk_fma_f32 v[94:95], v[56:57], v[94:95], v[6:7]
	v_pk_fma_f32 v[92:93], v[58:59], v[92:93], v[4:5]
	global_store_dwordx2 v[86:87], v[70:71], off offset:512
	v_cvt_pk_bf16_f32 v70, v92, v93
	v_cvt_pk_bf16_f32 v71, v94, v95
	s_mov_b64 vcc, s[4:5]
	v_pk_fma_f32 v[90:91], v[60:61], v[90:91], v[10:11]
	v_pk_fma_f32 v[96:97], v[62:63], v[96:97], v[8:9]
	global_store_dwordx2 v[86:87], v[70:71], off offset:1024
	v_cvt_pk_bf16_f32 v70, v96, v97
	v_cvt_pk_bf16_f32 v71, v90, v91
	global_store_dwordx2 v[86:87], v[70:71], off offset:1536
	s_cbranch_vccnz .LBB0_264
	s_waitcnt vmcnt(0)
	s_barrier
	s_and_saveexec_b64 s[4:5], s[26:27]
	s_xor_b64 s[38:39], exec, s[4:5]
	s_cbranch_execz .LBB0_310
	s_add_i32 s4, 0, 0x20020
	v_mov_b32_e32 v0, s4
	s_waitcnt vmcnt(0) expcnt(0) lgkmcnt(0)
	ds_read_b32 v2, v0
	s_add_i32 s4, 0, 0x20024
	v_mov_b32_e32 v0, s4
	ds_read_b32 v0, v0
	s_waitcnt lgkmcnt(1)
	v_cmp_ne_u32_e32 vcc, 0, v2
	s_cbranch_vccnz .LBB0_280
	s_add_u32 s4, s40, 0x80200
	s_addc_u32 s5, s41, 0
	s_add_u32 s8, s40, 0x80400
	s_addc_u32 s9, s41, 0
	s_add_u32 s10, s40, 0x80500
	s_addc_u32 s11, s41, 0
	s_add_u32 s12, s40, 0x80600
	s_addc_u32 s13, s41, 0
	s_add_u32 s14, s40, 0x80700
	s_addc_u32 s15, s41, 0
	s_add_u32 s16, s40, 0x80800
	s_addc_u32 s17, s41, 0
	s_add_u32 s18, s40, 0x80900
	s_addc_u32 s19, s41, 0
	s_add_u32 s20, s40, 0x80a00
	s_addc_u32 s21, s41, 0
	s_add_u32 s22, s40, 0x80b00
	s_addc_u32 s23, s41, 0
	s_add_u32 s28, s40, 0x80c00
	s_addc_u32 s29, s41, 0
	s_add_u32 s30, s40, 0x80d00
	s_addc_u32 s31, s41, 0
	s_add_u32 s34, s40, 0x80e00
	s_addc_u32 s35, s41, 0
	s_add_u32 s36, s40, 0x80f00
	s_addc_u32 s37, s41, 0
	s_add_u32 s56, s40, 0x81000
	s_addc_u32 s57, s41, 0
	s_add_u32 s58, s40, 0x81100
	s_addc_u32 s59, s41, 0
	s_add_u32 s60, s40, 0x81200
	s_addc_u32 s61, s41, 0
	s_add_u32 s62, s40, 0x81300
	s_mul_i32 s24, s43, s92
	s_addc_u32 s63, s41, 0
	s_mul_i32 s24, s24, s42
	s_mov_b32 s25, 1
	s_mov_b64 s[6:7], 0
	s_waitcnt lgkmcnt(0)
	v_mov_b64_e32 v[0:1], s[8:9]
	v_mov_b64_e32 v[2:3], s[10:11]
	v_mov_b64_e32 v[4:5], s[12:13]
	v_mov_b64_e32 v[6:7], s[14:15]
	v_mov_b64_e32 v[8:9], s[16:17]
	v_mov_b64_e32 v[10:11], s[18:19]
	v_mov_b64_e32 v[12:13], s[20:21]
	v_mov_b64_e32 v[14:15], s[22:23]
	v_mov_b64_e32 v[16:17], s[28:29]
	v_mov_b64_e32 v[18:19], s[30:31]
	v_mov_b64_e32 v[20:21], s[34:35]
	v_mov_b64_e32 v[22:23], s[36:37]
	v_mov_b64_e32 v[24:25], s[56:57]
	v_mov_b64_e32 v[26:27], s[58:59]
	v_mov_b64_e32 v[28:29], s[60:61]
	v_mov_b64_e32 v[30:31], s[62:63]
	s_branch .LBB0_270

; __global__ void __launch_bounds__(512) fwd_megakernel(Args args) {
;     ...
;         for (int qi = 0; qi < 8; ++qi) {
;             const unsigned xq = (myx + (unsigned)qi) & 7u;
;             unsigned* qctr = ctlw + CW_QUEUE + 64 * xq;
.LBB0_389:
	s_mov_b32 s98, 0
	s_add_i32 s3, s82, s29
	s_and_b32 s4, s3, 7
	s_lshl_b32 s4, s4, 8
	s_add_u32 s34, s65, s4
	s_addc_u32 s35, s66, 0
	s_bfe_u32 s4, s3, 0x20001
	s_and_b32 s83, s3, 1
	s_lshl_b32 s3, s4, 4
	s_lshl_b32 s5, s4, 22
	s_lshl_b32 s36, s4, 13
	s_mov_b32 s37, s9
	s_lshl_b32 s84, s3, 2
	s_lshl_b32 s85, s5, 1
	s_branch .LBB0_392

; #define tid (fresh_tid())
; __global__ void __launch_bounds__(512) fwd_megakernel(Args args) {
;     ...
;             for (;;) {
;                 if (tid == 0) *uslot = atomicAdd(qctr, 1u);
;                 __syncthreads();
;                 const unsigned u = *uslot;
;                 __syncthreads();
;                 if (u >= 128u) break;
.LBB0_392:
	v_mov_b32_e32 v0, v156
	s_nop 0
	v_cmp_eq_u32_e32 vcc, 0, v0
	s_and_saveexec_b64 s[4:5], vcc
	s_cbranch_execz .LBB0_394
	v_mov_b64_e32 v[2:3], s[34:35]
	s_cmp_eq_u32 s98, 0
	s_cbranch_scc0 .Lpq_d_have
	global_atomic_add v237, v[2:3], v151, off sc0
	s_mov_b32 s98, 1
	s_waitcnt vmcnt(0)
.Lpq_d_have:
	v_mov_b32_e32 v0, v237
	global_atomic_add v237, v[2:3], v151, off sc0
	ds_write_b32 v1, v0 offset:55424

; __device__ __forceinline__ float max3f(float a, float b, float c) { float r; asm("v_max3_f32 %0, %1, %2, %3" : "=v"(r) : "v"(a), "v"(b), "v"(c)); return r; }
; __device__ __forceinline__ float xhalf_max(float m) { auto rr = __builtin_amdgcn_permlane32_swap(__float_as_uint(m), __float_as_uint(m), false, false); return fmaxf(__uint_as_float(rr[0]), __uint_as_float(rr[1])); }
; template <int MODE, int DV> ...
;     ...
;                 float mx;
;                 { float a0 = max3f(p0[0], p0[1], p0[2]), a1 = max3f(p0[3], p0[4], p0[5]), a2 = max3f(p0[6], p0[7], p0[8]), a3 = max3f(p0[9], p0[10], p0[11]);
;                   float a4 = max3f(p0[12], p0[13], p0[14]), a5 = max3f(p0[15], p1[0], p1[1]), a6 = max3f(p1[2], p1[3], p1[4]), a7 = max3f(p1[5], p1[6], p1[7]);
;                   float a8 = max3f(p1[8], p1[9], p1[10]), a9 = max3f(p1[11], p1[12], p1[13]), a10 = max3f(p1[14], p1[15], a0);
;                   a1 = max3f(a1, a2, a3); a4 = max3f(a4, a5, a6); a7 = max3f(a7, a8, a9);
;                   mx = xhalf_max(max3f(max3f(a1, a4, a7), a10, a10)); }
;                 if (first || __any(mx > 6.0f)) {
;                     const float dl = first ? mx : fmaxf(mx, 0.f);
.LBB0_402:
	v_max3_f32 v143, v83, v84, v85
	v_max3_f32 v15, v80, v81, v82
	v_max3_f32 v169, v86, v87, v88
	v_max3_f32 v170, v89, v90, v91
	v_max3_f32 v171, v92, v93, v94
	v_max3_f32 v172, v95, v96, v97
	v_max3_f32 v173, v98, v99, v100
	v_max3_f32 v174, v101, v102, v103
	v_max3_f32 v175, v104, v105, v106
	s_nop 0
	v_max3_f32 v143, v143, v169, v170
	v_max3_f32 v176, v107, v108, v109
	v_max3_f32 v15, v110, v111, v15
	v_max3_f32 v169, v171, v172, v173
	s_xor_b64 s[48:49], s[6:7], -1
	v_max3_f32 v170, v174, v175, v176
	s_andn2_b64 vcc, exec, s[48:49]
	v_max3_f32 v143, v143, v169, v170
	s_mov_b64 s[56:57], -1
	v_max3_f32 v15, v143, v15, v15
	s_nop 0
	v_mov_b32_e32 v143, v15
	s_nop 1
	v_permlane32_swap_b32_e32 v15, v143
	v_max_f32_e32 v143, v143, v143
	v_max_f32_e32 v15, v15, v15
	v_max_f32_e32 v15, v15, v143
	s_cbranch_vccnz .LBB0_405
	v_cmp_lt_f32_e32 vcc, s81, v15
	s_cbranch_vccz .LBB0_409
	v_max_f32_e32 v15, v15, v15
	v_max_f32_e32 v15, 0, v15

; __device__ __forceinline__ float max3f(float a, float b, float c) { float r; asm("v_max3_f32 %0, %1, %2, %3" : "=v"(r) : "v"(a), "v"(b), "v"(c)); return r; }
; __device__ __forceinline__ float xhalf_max(float m) { auto rr = __builtin_amdgcn_permlane32_swap(__float_as_uint(m), __float_as_uint(m), false, false); return fmaxf(__uint_as_float(rr[0]), __uint_as_float(rr[1])); }
; template <int MODE, int DV> ...
;     ...
;                 { float a0 = max3f(p0[0], p0[1], p0[2]), a1 = max3f(p0[3], p0[4], p0[5]), a2 = max3f(p0[6], p0[7], p0[8]), a3 = max3f(p0[9], p0[10], p0[11]);
;                   float a4 = max3f(p0[12], p0[13], p0[14]), a5 = max3f(p0[15], p1[0], p1[1]), a6 = max3f(p1[2], p1[3], p1[4]), a7 = max3f(p1[5], p1[6], p1[7]);
;                   float a8 = max3f(p1[8], p1[9], p1[10]), a9 = max3f(p1[11], p1[12], p1[13]), a10 = max3f(p1[14], p1[15], a0);
;                   a1 = max3f(a1, a2, a3); a4 = max3f(a4, a5, a6); a7 = max3f(a7, a8, a9);
;                   mx = xhalf_max(max3f(max3f(a1, a4, a7), a10, a10)); }
;                 if (first || __any(mx > 6.0f)) {
;                     const float dl = first ? mx : fmaxf(mx, 0.f);
.LBB0_420:
	v_max3_f32 v143, v83, v84, v85
	v_max3_f32 v15, v80, v81, v82
	v_max3_f32 v169, v86, v87, v88
	v_max3_f32 v170, v89, v90, v91
	v_max3_f32 v171, v92, v93, v94
	v_max3_f32 v172, v95, v96, v97
	v_max3_f32 v173, v98, v99, v100
	v_max3_f32 v174, v101, v102, v103
	v_max3_f32 v175, v104, v105, v106
	s_nop 0
	v_max3_f32 v143, v143, v169, v170
	v_max3_f32 v176, v107, v108, v109
	v_max3_f32 v15, v110, v111, v15
	v_max3_f32 v169, v171, v172, v173
	s_xor_b64 s[48:49], s[6:7], -1
	v_max3_f32 v170, v174, v175, v176
	s_andn2_b64 vcc, exec, s[48:49]
	v_max3_f32 v143, v143, v169, v170
	s_mov_b64 s[58:59], -1
	v_max3_f32 v15, v143, v15, v15
	s_nop 0
	v_mov_b32_e32 v143, v15
	s_nop 1
	v_permlane32_swap_b32_e32 v15, v143
	v_max_f32_e32 v143, v143, v143
	v_max_f32_e32 v15, v15, v15
	v_max_f32_e32 v15, v15, v143
	s_cbranch_vccnz .LBB0_423
	v_cmp_lt_f32_e32 vcc, s81, v15
	s_cbranch_vccz .LBB0_427
	v_max_f32_e32 v15, v15, v15
	v_max_f32_e32 v15, 0, v15

; #define LAS __attribute__((address_space(3)))
; __global__ void __launch_bounds__(512) fwd_megakernel(Args args) {
;     ...
;         {
;             unsigned* qctr = ctlw + CW_QUEUE + 64 * 8;
;             volatile LAS unsigned* sslot = MISC + 40; LAS unsigned* sflags = (LAS unsigned*)(lds + GEMM_LDS) + 44;
;             for (;;) {
.LBB0_435:
	s_mov_b32 s98, 0
	s_add_u32 s34, s40, 0x84900
	s_addc_u32 s35, s41, 0
	s_add_i32 s45, 0, 0x200a0
	s_mov_b32 s57, 0
	v_mov_b32_e32 v125, 1
	v_mov_b32_e32 v134, s45
	s_movk_i32 s77, 0x3ff
	v_mov_b32_e32 v1, 0
	s_movk_i32 s78, 0x90
	s_mov_b64 s[58:59], 0x1c000000
	s_mov_b32 s79, 0x20000
	s_mov_b32 s80, 0x80000
	s_add_i32 s81, 0, 0x200b0
	s_mov_b32 s36, 0x3f803f80
	s_mov_b32 s82, 0xc2400000
	s_mov_b64 s[60:61], 0x1e000000
	v_mov_b32_e32 v135, 0x3f80
	s_branch .LBB0_438

; #define tid (fresh_tid())
; __global__ void __launch_bounds__(512) fwd_megakernel(Args args) {
;     ...
;             for (;;) {
;                 if (tid == 0) sslot[0] = atomicAdd(qctr, 1u);
;                 __syncthreads();
;                 const unsigned u = sslot[0];
;                 __syncthreads();
;                 if (u >= 1024u) break;
.LBB0_438:
	v_mov_b32_e32 v0, v156
	s_nop 0
	v_cmp_eq_u32_e32 vcc, 0, v0
	s_and_saveexec_b64 s[4:5], vcc
	s_cbranch_execz .LBB0_440
	v_mov_b64_e32 v[2:3], s[34:35]
	s_cmp_eq_u32 s98, 0
	s_cbranch_scc0 .Lpq_s_have
	global_atomic_add v238, v[2:3], v125, off sc0
	s_mov_b32 s98, 1
	s_waitcnt vmcnt(0)
.Lpq_s_have:
	v_mov_b32_e32 v0, v238
	global_atomic_add v238, v[2:3], v125, off sc0
	v_mov_b32_e32 v2, s45
	ds_write_b32 v2, v0

; #define LAS __attribute__((address_space(3)))
; #define tid (fresh_tid())
; __global__ void __launch_bounds__(512) fwd_megakernel(Args args) {
;     ...
;         {
;             constexpr int I_G2 = (DM / 64) * (DFF / 32), I_OUT2 = (DM / 64) * (DM / 32), NLATE = 3 * I_G2 + I_OUT2;
;             unsigned* tq = ctlw + CW_QUEUE + 64 * 9;
;             volatile LAS unsigned* tslot = MISC + 32;
;             LAS float* scr = (LAS float*)(lds + wave * 16384);
;             for (;;) {
;                 if (tid == 0) tslot[0] = atomicAdd(tq, 1u);
;                 __syncthreads();
.LBB0_461:
	s_mov_b32 s98, 0
	s_add_u32 s4, s40, 0x84a00
	s_addc_u32 s5, s41, 0
	s_add_i32 s14, 0, 0x20080
	v_mov_b32_e32 v2, 1
	v_mov_b32_e32 v3, s14
	v_mov_b32_e32 v1, 0
	s_mov_b64 s[6:7], 0x2500000
	s_mov_b64 s[8:9], 0x1a00000
	s_mov_b64 s[10:11], 0x1800000
	s_branch .LBB0_464

; #define tid (fresh_tid())
; __global__ void __launch_bounds__(512) fwd_megakernel(Args args) {
;     ...
;             for (;;) {
;                 if (tid == 0) tslot[0] = atomicAdd(tq, 1u);
;                 __syncthreads();
;                 const unsigned ch = tslot[0];
;                 __syncthreads();
;                 if (ch * 8u >= (unsigned)NLATE) break;
.LBB0_464:
	v_mov_b32_e32 v0, v156
	s_nop 0
	v_cmp_eq_u32_e32 vcc, 0, v0
	s_and_saveexec_b64 s[12:13], vcc
	s_cbranch_execz .LBB0_466
	v_mov_b64_e32 v[4:5], s[4:5]
	s_cmp_eq_u32 s98, 0
	s_cbranch_scc0 .Lpq_t_have
	global_atomic_add v239, v[4:5], v2, off sc0
	s_mov_b32 s98, 1
	s_waitcnt vmcnt(0)
.Lpq_t_have:
	s_waitcnt vmcnt(0)
	v_mov_b32_e32 v0, v239
	global_atomic_add v239, v[4:5], v2, off sc0
	v_mov_b32_e32 v4, s14
	ds_write_b32 v4, v0

; #define GAS __attribute__((address_space(1)))
; __device__ __forceinline__ float wave_sum(float v) { return xrow_sum(row16_sum(v)); }
; __device__ __forceinline__ unsigned pk_bf16(float lo, float hi) { return pg8::cvt_pk_bf16(lo, hi); }
; __device__ __forceinline__ void rowpass_attn(const float* __restrict__ Od, const bf16* __restrict__ Os, bf16* __restrict__ H, const float* __restrict__ subln,
;                                              const float* __restrict__ sbeta, float lam, int gw, int lane) {
;     ...
;     for (int row = row_lo; row < row_lo + RPW; ++row) {
;         const u32x4 w0 = n0, w1 = n1, ws = ns;
;         { const int rn = (row + 1 < row_lo + RPW) ? row + 1 : row;
;           n0 = __builtin_nontemporal_load((const GAS u32x4*)((const bf16*)Od + (size_t)rn * 1024 + hd * 256 + e0)); n1 = __builtin_nontemporal_load((const GAS u32x4*)((const bf16*)Od + (size_t)rn * 1024 + hd * 256 + 128 + e0));
;           ns = __builtin_nontemporal_load((const GAS u32x4*)(Os + (size_t)rn * 512 + 8 * lane)); }
;         float a0[8], a1[8], v[8], sv[8];
;         RA_UNPK(w0, a0); RA_UNPK(w1, a1); RA_UNPK(ws, sv);
;         float ss = 0.f, s2 = 0.f;
; #pragma unroll
;         for (int i = 0; i < 8; ++i) { v[i] = a0[i] - a1[i] * lam; ss += v[i] * v[i]; s2 += sv[i] * sv[i]; }
;         ss = row16_sum(ss);
;         const float rstd = 0.8f / sqrtf(ss * (1.0f / 128.0f) + RMS_EPS);
;         u32x4 od; od.x = pk_bf16(v[0] * rstd * sl0.x, v[1] * rstd * sl0.y); od.y = pk_bf16(v[2] * rstd * sl0.z, v[3] * rstd * sl0.w);
;         od.z = pk_bf16(v[4] * rstd * sl1.x, v[5] * rstd * sl1.y); od.w = pk_bf16(v[6] * rstd * sl1.z, v[7] * rstd * sl1.w);
;         *(GAS u32x4*)(H + (size_t)row * 1024 + hd * 128 + e0) = od;
;         const float rstd2 = 1.0f / sqrtf(wave_sum(s2) * (1.0f / 512.0f) + RMS_EPS);
;         u32x4 o; o.x = pk_bf16(sv[0] * rstd2 * be0.x, sv[1] * rstd2 * be0.y); o.y = pk_bf16(sv[2] * rstd2 * be0.z, sv[3] * rstd2 * be0.w);
;         o.z = pk_bf16(sv[4] * rstd2 * be1.x, sv[5] * rstd2 * be1.y); o.w = pk_bf16(sv[6] * rstd2 * be1.z, sv[7] * rstd2 * be1.w);
;         *(GAS u32x4*)(H + (size_t)row * 1024 + 512 + 8 * lane) = o;
;     }
.LBB0_525:
	s_add_i32 s7, s14, 1
	s_cmp_lt_i32 s14, s70
	s_cselect_b64 s[4:5], -1, 0
	s_and_b64 s[4:5], s[4:5], exec
	s_cselect_b32 s6, s7, s14
	s_mov_b32 s14, s7
	s_ashr_i32 s7, s6, 31
	s_waitcnt vmcnt(0)
	v_lshlrev_b32_e32 v40, 16, v25
	v_lshlrev_b32_e32 v41, 16, v26
	v_lshlrev_b32_e32 v44, 16, v17
	v_lshlrev_b32_e32 v45, 16, v18
	s_lshl_b64 s[8:9], s[6:7], 11
	v_lshlrev_b32_e32 v39, 16, v24
	v_and_b32_e32 v24, 0xffff0000, v24
	v_and_b32_e32 v25, 0xffff0000, v25
	v_and_b32_e32 v26, 0xffff0000, v26
	v_lshlrev_b32_e32 v42, 16, v27
	v_and_b32_e32 v27, 0xffff0000, v27
	v_lshlrev_b32_e32 v43, 16, v16
	v_and_b32_e32 v16, 0xffff0000, v16
	v_and_b32_e32 v17, 0xffff0000, v17
	v_and_b32_e32 v18, 0xffff0000, v18
	v_lshlrev_b32_e32 v46, 16, v19
	v_and_b32_e32 v19, 0xffff0000, v19
	s_waitcnt lgkmcnt(0)
	v_fma_f32 v44, -v36, v44, v40
	v_fma_f32 v45, -v36, v45, v41
	s_lshl_b64 s[6:7], s[6:7], 10
	v_lshl_add_u64 v[40:41], v[30:31], 0, s[8:9]
	v_lshlrev_b32_e32 v47, 16, v20
	v_and_b32_e32 v48, 0xffff0000, v20
	v_lshlrev_b32_e32 v49, 16, v21
	v_and_b32_e32 v50, 0xffff0000, v21
	v_lshlrev_b32_e32 v51, 16, v22
	v_and_b32_e32 v52, 0xffff0000, v22
	v_lshlrev_b32_e32 v53, 16, v23
	v_and_b32_e32 v54, 0xffff0000, v23
	v_fma_f32 v39, -v36, v43, v39
	v_fma_f32 v55, -v36, v16, v24
	v_fma_f32 v57, -v36, v17, v25
	v_fma_f32 v58, -v36, v18, v26
	v_fma_f32 v46, -v36, v46, v42
	v_fma_f32 v59, -v36, v19, v27
	v_lshl_add_u64 v[42:43], v[28:29], 0, s[6:7]
	s_mov_b64 exec, s[4:5]
	global_load_dwordx4 v[24:27], v[40:41], off nt
	global_load_dwordx4 v[16:19], v[40:41], off offset:256 nt
	global_load_dwordx4 v[20:23], v[42:43], off nt
	s_mov_b64 exec, -1
	s_nop 4
	v_mul_f32_e32 v56, v48, v48
	v_mul_f32_e32 v60, v55, v55
	v_fmac_f32_e32 v56, v47, v47
	v_fmac_f32_e32 v60, v39, v39
	v_fmac_f32_e32 v56, v49, v49
	v_fmac_f32_e32 v60, v44, v44
	v_fmac_f32_e32 v56, v50, v50
	v_fmac_f32_e32 v60, v57, v57
	v_fmac_f32_e32 v56, v51, v51
	v_fmac_f32_e32 v60, v45, v45
	v_fmac_f32_e32 v56, v52, v52
	v_fmac_f32_e32 v60, v58, v58
	v_fmac_f32_e32 v56, v53, v53
	v_fmac_f32_e32 v60, v46, v46
	v_fmac_f32_e32 v56, v54, v54
	v_fmac_f32_e32 v60, v59, v59
	s_nop 0
	v_add_f32_dpp v40, v56, v56 quad_perm:[1,0,3,2] row_mask:0xf bank_mask:0xf bound_ctrl:1
	v_add_f32_dpp v41, v60, v60 quad_perm:[1,0,3,2] row_mask:0xf bank_mask:0xf bound_ctrl:1
	s_nop 0
	v_add_f32_dpp v40, v40, v40 quad_perm:[2,3,0,1] row_mask:0xf bank_mask:0xf bound_ctrl:1
	v_add_f32_dpp v41, v41, v41 quad_perm:[2,3,0,1] row_mask:0xf bank_mask:0xf bound_ctrl:1
	s_nop 0
	v_add_f32_dpp v40, v40, v40 row_half_mirror row_mask:0xf bank_mask:0xf bound_ctrl:1
	v_add_f32_dpp v41, v41, v41 row_half_mirror row_mask:0xf bank_mask:0xf bound_ctrl:1
	s_nop 0
	v_add_f32_dpp v40, v40, v40 row_mirror row_mask:0xf bank_mask:0xf bound_ctrl:1
	v_add_f32_dpp v41, v41, v41 row_mirror row_mask:0xf bank_mask:0xf bound_ctrl:1
	v_mov_b32_e32 v42, v40
	v_fmamk_f32 v41, v41, 0x3c000000, v37
	s_nop 0
	v_permlane16_swap_b32_e32 v40, v42
	v_mul_f32_e32 v43, 0x4f800000, v41
	v_cmp_gt_f32_e32 vcc, s12, v41
	v_add_f32_e32 v40, v40, v42
	v_mov_b32_e32 v42, v40
	v_cndmask_b32_e32 v41, v41, v43, vcc
	v_sqrt_f32_e32 v43, v41
	v_permlane32_swap_b32_e32 v40, v42
	v_add_f32_e32 v40, v40, v42
	v_fmamk_f32 v40, v40, 0x3b000000, v37
	v_mul_f32_e32 v42, 0x4f800000, v40
	v_cmp_gt_f32_e64 s[6:7], s12, v40
	v_add_u32_e32 v56, -1, v43
	v_add_u32_e32 v60, 1, v43
	v_cndmask_b32_e64 v40, v40, v42, s[6:7]
	v_fma_f32 v42, -v56, v43, v41
	v_fma_f32 v61, -v60, v43, v41
	v_cmp_ge_f32_e64 s[8:9], 0, v42
	v_sqrt_f32_e32 v62, v40
	s_nop 0
	v_cndmask_b32_e64 v42, v43, v56, s[8:9]
	v_cmp_lt_f32_e64 s[8:9], 0, v61
	v_add_u32_e32 v56, 1, v62
	s_nop 0
	v_cndmask_b32_e64 v42, v42, v60, s[8:9]
	v_mul_f32_e32 v43, 0x37800000, v42
	v_cndmask_b32_e32 v42, v42, v43, vcc
	v_cmp_class_f32_e32 vcc, v41, v38
	v_add_u32_e32 v43, -1, v62
	v_fma_f32 v60, -v56, v62, v40
	v_cndmask_b32_e32 v41, v42, v41, vcc
	v_fma_f32 v42, -v43, v62, v40
	v_div_scale_f32 v61, s[8:9], v41, v41, s13
	v_cmp_ge_f32_e64 s[8:9], 0, v42
	v_div_scale_f32 v63, vcc, s13, v41, s13
	s_nop 0
	v_cndmask_b32_e64 v42, v62, v43, s[8:9]
	v_cmp_lt_f32_e64 s[8:9], 0, v60
	v_rcp_f32_e32 v43, v61
	s_nop 0
	v_cndmask_b32_e64 v42, v42, v56, s[8:9]
	v_mul_f32_e32 v56, 0x37800000, v42
	v_cndmask_b32_e64 v42, v42, v56, s[6:7]
	v_cmp_class_f32_e64 s[6:7], v40, v38
	s_nop 1
	v_cndmask_b32_e64 v56, v42, v40, s[6:7]
	v_fma_f32 v40, -v61, v43, 1.0
	v_div_scale_f32 v60, s[6:7], v56, v56, 1.0
	v_fmac_f32_e32 v43, v40, v43
	v_rcp_f32_e32 v64, v60
	v_mul_f32_e32 v40, v63, v43
	v_fma_f32 v42, -v61, v40, v63
	v_fmac_f32_e32 v40, v42, v43
	v_fma_f32 v42, -v61, v40, v63
	v_fma_f32 v61, -v60, v64, 1.0
	v_div_scale_f32 v62, s[6:7], 1.0, v56, 1.0
	v_div_fmas_f32 v40, v42, v43, v40
	v_fmac_f32_e32 v64, v61, v64
	v_div_fixup_f32 v40, v40, v41, s13
	v_mul_f32_e32 v61, v62, v64
	v_mul_f32_e32 v39, v39, v40
	v_mul_f32_e32 v41, v55, v40
	v_fma_f32 v55, -v60, v61, v62
	v_mul_f32_e32 v42, v44, v40
	v_mul_f32_e32 v43, v57, v40
	v_mul_f32_e32 v44, v45, v40
	v_mul_f32_e32 v45, v58, v40
	v_mul_f32_e32 v46, v46, v40
	v_mul_f32_e32 v40, v59, v40
	v_mul_f32_e32 v39, v0, v39
	v_fmac_f32_e32 v61, v55, v64
	v_mul_f32_e32 v41, v1, v41
	v_mul_f32_e32 v57, v7, v40
	v_cvt_pk_bf16_f32 v40, v39, v41
	v_fma_f32 v39, -v60, v61, v62
	s_mov_b64 vcc, s[6:7]
	v_mul_f32_e32 v42, v2, v42
	v_mul_f32_e32 v43, v3, v43
	v_div_fmas_f32 v39, v39, v64, v61
	v_mul_f32_e32 v44, v4, v44
	v_mul_f32_e32 v45, v5, v45
	v_mul_f32_e32 v46, v6, v46
	v_cvt_pk_bf16_f32 v41, v42, v43
	v_cvt_pk_bf16_f32 v42, v44, v45
	v_cvt_pk_bf16_f32 v43, v46, v57
	v_div_fixup_f32 v39, v39, v56, 1.0
	global_store_dwordx4 v[34:35], v[40:43], off
	v_mul_f32_e32 v44, v39, v51
	v_mul_f32_e32 v45, v39, v52
	v_mul_f32_e32 v40, v39, v47
	v_mul_f32_e32 v41, v39, v48
	v_mul_f32_e32 v42, v39, v49
	v_mul_f32_e32 v43, v39, v50
	v_mul_f32_e32 v46, v39, v53
	v_mul_f32_e32 v39, v39, v54
	v_mul_f32_e32 v40, v8, v40
	v_mul_f32_e32 v41, v9, v41
	v_mul_f32_e32 v42, v10, v42
	v_mul_f32_e32 v43, v11, v43
	v_lshl_add_u64 v[34:35], v[34:35], 0, s[10:11]
	v_mul_f32_e32 v44, v12, v44
	v_mul_f32_e32 v45, v13, v45
	v_mul_f32_e32 v46, v14, v46
	v_mul_f32_e32 v39, v15, v39
	v_cvt_pk_bf16_f32 v40, v40, v41
	v_cvt_pk_bf16_f32 v41, v42, v43
	v_cvt_pk_bf16_f32 v42, v44, v45
	v_cvt_pk_bf16_f32 v43, v46, v39
	global_store_dwordx4 v[32:33], v[40:43], off
	v_lshl_add_u64 v[32:33], v[32:33], 0, s[10:11]
	s_mov_b64 vcc, s[4:5]
	s_cbranch_vccnz .LBB0_525
; __device__ __forceinline__ unsigned xb_ld(unsigned* p)              { return __hip_atomic_load(p, __ATOMIC_RELAXED, __HIP_MEMORY_SCOPE_AGENT); }
; __device__ __forceinline__ void xcd_barrier_complete(unsigned* bar, unsigned x, unsigned& nloc, unsigned& nx) {
;     const unsigned G = gridDim.x * gridDim.y * gridDim.z;
;     unsigned sum, cnt, mine, sp = 0u;
;     for (;;) {
;         sum = 0u; cnt = 0u; mine = 0u;
; #pragma unroll
;         for (unsigned j = 0; j < 16; ++j) { const unsigned c = xb_ld(&bar[XB_XCNT(j)]); sum += c; cnt += (c > 0u) ? 1u : 0u; mine = (j == x) ? c : mine; }
; __device__ __forceinline__ void xcd_barrier(const XcdBarrier& b) {
;     asm volatile("s_waitcnt vmcnt(0)" ::: "memory");
;     __syncthreads();
;     if (threadIdx.x == 0) {
;         unsigned* bar = b.bar;
;         __builtin_amdgcn_s_waitcnt(0);
;         unsigned nloc = b.st[0], nx = b.st[1];
;         if (nloc == 0u) { xcd_barrier_complete(bar, b.x, nloc, nx); b.st[0] = nloc; b.st[1] = nx; }
	s_waitcnt vmcnt(0)
	s_barrier
	s_and_saveexec_b64 s[4:5], s[26:27]
	s_xor_b64 s[38:39], exec, s[4:5]
	s_cbranch_execz .LBB0_571
	s_add_i32 s3, 0, 0x20020
	v_mov_b32_e32 v0, s3
	s_waitcnt vmcnt(0) expcnt(0) lgkmcnt(0)
	ds_read_b32 v2, v0
	s_add_i32 s3, 0, 0x20024
	v_mov_b32_e32 v0, s3
	ds_read_b32 v0, v0
	s_waitcnt lgkmcnt(1)
	v_cmp_ne_u32_e32 vcc, 0, v2
	s_cbranch_vccnz .LBB0_541
	s_add_u32 s4, s40, 0x80200
	s_addc_u32 s5, s41, 0
	s_add_u32 s8, s40, 0x80400
	s_addc_u32 s9, s41, 0
	s_add_u32 s10, s40, 0x80500
	s_addc_u32 s11, s41, 0
	s_add_u32 s12, s40, 0x80600
	s_addc_u32 s13, s41, 0
	s_add_u32 s14, s40, 0x80700
	s_addc_u32 s15, s41, 0
	s_add_u32 s16, s40, 0x80800
	s_addc_u32 s17, s41, 0
	s_add_u32 s18, s40, 0x80900
	s_addc_u32 s19, s41, 0
	s_add_u32 s20, s40, 0x80a00
	s_addc_u32 s21, s41, 0
	s_add_u32 s22, s40, 0x80b00
	s_addc_u32 s23, s41, 0
	s_add_u32 s28, s40, 0x80c00
	s_addc_u32 s29, s41, 0
	s_add_u32 s30, s40, 0x80d00
	s_addc_u32 s31, s41, 0
	s_add_u32 s34, s40, 0x80e00
	s_addc_u32 s35, s41, 0
	s_add_u32 s36, s40, 0x80f00
	s_addc_u32 s37, s41, 0
	s_add_u32 s48, s40, 0x81000
	s_addc_u32 s49, s41, 0
	s_add_u32 s56, s40, 0x81100
	s_addc_u32 s57, s41, 0
	s_add_u32 s58, s40, 0x81200
	s_addc_u32 s59, s41, 0
	s_add_u32 s60, s40, 0x81300
	s_mul_i32 s24, s43, s92
	s_addc_u32 s61, s41, 0
	s_mul_i32 s24, s24, s42
	s_mov_b32 s25, 1
	s_mov_b64 s[6:7], 0
	s_waitcnt lgkmcnt(0)
	v_mov_b64_e32 v[0:1], s[8:9]
	v_mov_b64_e32 v[2:3], s[10:11]
	v_mov_b64_e32 v[4:5], s[12:13]
	v_mov_b64_e32 v[6:7], s[14:15]
	v_mov_b64_e32 v[8:9], s[16:17]
	v_mov_b64_e32 v[10:11], s[18:19]
	v_mov_b64_e32 v[12:13], s[20:21]
	v_mov_b64_e32 v[14:15], s[22:23]
	v_mov_b64_e32 v[16:17], s[28:29]
	v_mov_b64_e32 v[18:19], s[30:31]
	v_mov_b64_e32 v[20:21], s[34:35]
	v_mov_b64_e32 v[22:23], s[36:37]
	v_mov_b64_e32 v[24:25], s[48:49]
	v_mov_b64_e32 v[26:27], s[56:57]
	v_mov_b64_e32 v[28:29], s[58:59]
	v_mov_b64_e32 v[30:31], s[60:61]
	s_branch .LBB0_531

; #define GAS __attribute__((address_space(1)))
; __device__ __forceinline__ float wave_sum(float v) { return xrow_sum(row16_sum(v)); }
; __device__ __forceinline__ unsigned pk_bf16(float lo, float hi) { return pg8::cvt_pk_bf16(lo, hi); }
; template <bool HAS_F, bool HAS_H, bool XIN_B = false, bool XOUT_B = false> ...
;     ...
;     for (int row = row_lo; row < row_lo + RPW; ++row) {
;         f32x4 x[4]; u32x2 fwv[4];
; #pragma unroll
;         for (int j = 0; j < 4; ++j) { x[j] = xn[j]; if (HAS_F) fwv[j] = fn[j]; }
;         { const int rn = (row + 1 < row_lo + RPW) ? row + 1 : row;
; #pragma unroll
;           for (int j = 0; j < 4; ++j) { RP_LDX(xn[j], rn, j); if (HAS_F) fn[j] = __builtin_nontemporal_load((const GAS u32x2*)(Fb + (size_t)rn * DM + 256 * j + 4 * lane)); } }
;         if (HAS_F) {
;             f32x4 f[4]; float ss = 0.f;
; #pragma unroll
;             for (int j = 0; j < 4; ++j) { const u32x2 fw = fwv[j];
;                 f[j] = (f32x4){__uint_as_float(fw.x << 16), __uint_as_float(fw.x & 0xffff0000u), __uint_as_float(fw.y << 16), __uint_as_float(fw.y & 0xffff0000u)}; ss += (f[j].x * f[j].x + f[j].y * f[j].y) + (f[j].z * f[j].z + f[j].w * f[j].w); }
;             const float rstd = 1.0f / sqrtf(wave_sum(ss) * (1.0f / DM) + RMS_EPS);
; #pragma unroll
;             for (int j = 0; j < 4; ++j) { x[j] = x[j] + f[j] * rstd * Cg[j];
;                 if (XOUT_B) { u32x2 w; w.x = pk_bf16(x[j].x, x[j].y); w.y = pk_bf16(x[j].z, x[j].w); *(GAS u32x2*)(xoutb + (size_t)row * DM + 256 * j + 4 * lane) = w;
;                     x[j] = (f32x4){__uint_as_float(w.x << 16), __uint_as_float(w.x & 0xffff0000u), __uint_as_float(w.y << 16), __uint_as_float(w.y & 0xffff0000u)}; }
;                 else __builtin_nontemporal_store(x[j], (GAS f32x4*)(xout + (size_t)row * DM + 256 * j + 4 * lane)); }
;         }
.LBB0_637:
	v_lshl_add_u64 v[86:87], s[10:11], 0, v[16:17]
	s_add_i32 s6, s15, 1
	v_lshlrev_b32_e32 v70, 16, v72
	v_and_b32_e32 v71, 0xffff0000, v72
	v_lshlrev_b32_e32 v72, 16, v73
	v_and_b32_e32 v73, 0xffff0000, v73
	v_lshlrev_b32_e32 v74, 16, v76
	v_and_b32_e32 v75, 0xffff0000, v76
	v_lshlrev_b32_e32 v76, 16, v77
	v_and_b32_e32 v77, 0xffff0000, v77
	v_add_co_u32_e32 v92, vcc, s13, v86
	v_lshlrev_b32_e32 v78, 16, v80
	v_and_b32_e32 v79, 0xffff0000, v80
	v_lshlrev_b32_e32 v80, 16, v81
	v_and_b32_e32 v81, 0xffff0000, v81
	v_lshl_add_u64 v[90:91], s[8:9], 0, v[16:17]
	s_cmp_lt_i32 s15, s70
	v_mul_f32_e32 v94, v71, v71
	v_mul_f32_e32 v95, v73, v73
	v_mul_f32_e32 v96, v75, v75
	v_mul_f32_e32 v97, v77, v77
	v_addc_co_u32_e32 v93, vcc, 0, v87, vcc
	v_lshlrev_b32_e32 v82, 16, v84
	v_and_b32_e32 v83, 0xffff0000, v84
	v_lshlrev_b32_e32 v84, 16, v85
	v_and_b32_e32 v85, 0xffff0000, v85
	v_mul_f32_e32 v98, v79, v79
	v_mul_f32_e32 v99, v81, v81
	v_add_co_u32_e32 v86, vcc, s14, v90
	s_cselect_b64 s[4:5], -1, 0
	v_fmac_f32_e32 v94, v70, v70
	v_fmac_f32_e32 v95, v72, v72
	v_fmac_f32_e32 v96, v74, v74
	v_fmac_f32_e32 v97, v76, v76
	v_mul_f32_e32 v100, v83, v83
	v_mul_f32_e32 v101, v85, v85
	v_addc_co_u32_e32 v87, vcc, 0, v91, vcc
	v_fmac_f32_e32 v98, v78, v78
	v_fmac_f32_e32 v99, v80, v80
	s_and_b64 s[4:5], s[4:5], exec
	v_add_f32_e32 v90, v94, v95
	v_add_f32_e32 v91, v96, v97
	v_fmac_f32_e32 v100, v82, v82
	v_fmac_f32_e32 v101, v84, v84
	v_add_f32_e32 v94, v98, v99
	s_cselect_b32 s16, s6, s15
	v_add_f32_e32 v90, v91, v90
	v_add_f32_e32 v95, v100, v101
	s_ashr_i32 s17, s16, 31
	v_add_f32_e32 v90, v94, v90
	s_mov_b32 s15, s6
	s_lshl_b64 s[6:7], s[16:17], 11
	v_add_f32_e32 v96, v95, v90
	v_lshl_add_u64 v[90:91], v[50:51], 0, s[6:7]
	v_lshl_add_u64 v[94:95], v[52:53], 0, s[6:7]
	v_add_f32_dpp v112, v96, v96 quad_perm:[1,0,3,2] row_mask:0xf bank_mask:0xf bound_ctrl:1
	s_mov_b64 exec, s[4:5]
	global_load_dwordx2 v[96:97], v[90:91], off nt
	global_load_dwordx2 v[98:99], v[90:91], off offset:512 nt
	global_load_dwordx2 v[100:101], v[90:91], off offset:1024 nt
	global_load_dwordx2 v[102:103], v[90:91], off offset:1536 nt
	global_load_dwordx2 v[104:105], v[94:95], off nt
	global_load_dwordx2 v[106:107], v[94:95], off offset:512 nt
	global_load_dwordx2 v[108:109], v[94:95], off offset:1024 nt
	global_load_dwordx2 v[110:111], v[94:95], off offset:1536 nt
	s_mov_b64 exec, -1
	s_nop 4
	v_add_f32_dpp v90, v112, v112 quad_perm:[2,3,0,1] row_mask:0xf bank_mask:0xf bound_ctrl:1
	s_add_u32 s8, s8, 0x800
	s_addc_u32 s9, s9, 0
	v_add_f32_dpp v90, v90, v90 row_half_mirror row_mask:0xf bank_mask:0xf bound_ctrl:1
	s_add_u32 s10, s10, 0x800
	s_addc_u32 s11, s11, 0
	v_add_f32_dpp v90, v90, v90 row_mirror row_mask:0xf bank_mask:0xf bound_ctrl:1
	v_mov_b32_e32 v91, v90
	s_nop 1
	v_permlane16_swap_b32_e32 v90, v91
	v_add_f32_e32 v90, v90, v91
	v_mov_b32_e32 v91, v90
	s_nop 1
	v_permlane32_swap_b32_e32 v90, v91
	v_add_f32_e32 v90, v90, v91
	v_fmamk_f32 v90, v90, 0x3a800000, v88
	v_mul_f32_e32 v91, 0x4f800000, v90
	v_cmp_gt_f32_e32 vcc, s12, v90
	s_nop 1
	v_cndmask_b32_e32 v90, v90, v91, vcc
	v_sqrt_f32_e32 v91, v90
	s_nop 0
	v_add_u32_e32 v94, -1, v91
	v_add_u32_e32 v95, 1, v91
	v_fma_f32 v112, -v94, v91, v90
	v_fma_f32 v113, -v95, v91, v90
	v_cmp_ge_f32_e64 s[6:7], 0, v112
	s_nop 1
	v_cndmask_b32_e64 v91, v91, v94, s[6:7]
	v_cmp_lt_f32_e64 s[6:7], 0, v113
	s_nop 1
	v_cndmask_b32_e64 v91, v91, v95, s[6:7]
	v_mul_f32_e32 v94, 0x37800000, v91
	v_cndmask_b32_e32 v91, v91, v94, vcc
	v_cmp_class_f32_e32 vcc, v90, v89
	s_nop 1
	v_cndmask_b32_e32 v90, v91, v90, vcc
	v_div_scale_f32 v91, s[6:7], v90, v90, 1.0
	v_rcp_f32_e32 v95, v91
	v_div_scale_f32 v94, vcc, 1.0, v90, 1.0
	v_fma_f32 v112, -v91, v95, 1.0
	v_fmac_f32_e32 v95, v112, v95
	v_mul_f32_e32 v112, v94, v95
	v_fma_f32 v113, -v91, v112, v94
	v_fmac_f32_e32 v112, v113, v95
	v_fma_f32 v91, -v91, v112, v94
	v_div_fmas_f32 v91, v91, v95, v112
	v_div_fixup_f32 v90, v91, v90, 1.0
	v_pk_mul_f32 v[70:71], v[70:71], v[90:91] op_sel_hi:[1,0]
	v_pk_mul_f32 v[72:73], v[72:73], v[90:91] op_sel_hi:[1,0]
	v_pk_fma_f32 v[54:55], v[20:21], v[70:71], v[54:55]
	v_pk_mul_f32 v[74:75], v[74:75], v[90:91] op_sel_hi:[1,0]
	v_pk_mul_f32 v[76:77], v[76:77], v[90:91] op_sel_hi:[1,0]
	v_pk_fma_f32 v[56:57], v[18:19], v[72:73], v[56:57]
	v_cvt_pk_bf16_f32 v54, v54, v55
	v_pk_mul_f32 v[78:79], v[78:79], v[90:91] op_sel_hi:[1,0]
	v_cvt_pk_bf16_f32 v55, v56, v57
	v_pk_mul_f32 v[80:81], v[80:81], v[90:91] op_sel_hi:[1,0]
	v_pk_mul_f32 v[82:83], v[82:83], v[90:91] op_sel_hi:[1,0]
	v_pk_fma_f32 v[60:61], v[42:43], v[76:77], v[60:61]
	v_pk_fma_f32 v[58:59], v[44:45], v[74:75], v[58:59]
	global_store_dwordx2 v[92:93], v[54:55], off
	v_lshlrev_b32_e32 v70, 16, v54
	v_and_b32_e32 v71, 0xffff0000, v54
	v_lshlrev_b32_e32 v74, 16, v55
	v_and_b32_e32 v75, 0xffff0000, v55
	v_cvt_pk_bf16_f32 v54, v58, v59
	v_cvt_pk_bf16_f32 v55, v60, v61
	v_pk_mul_f32 v[84:85], v[84:85], v[90:91] op_sel_hi:[1,0]
	v_pk_fma_f32 v[64:65], v[22:23], v[80:81], v[64:65]
	v_pk_fma_f32 v[62:63], v[24:25], v[78:79], v[62:63]
	v_pk_fma_f32 v[66:67], v[48:49], v[82:83], v[66:67]
	global_store_dwordx2 v[92:93], v[54:55], off offset:512
	v_lshlrev_b32_e32 v78, 16, v54
	v_and_b32_e32 v79, 0xffff0000, v54
	v_lshlrev_b32_e32 v82, 16, v55
	v_and_b32_e32 v83, 0xffff0000, v55
	v_cvt_pk_bf16_f32 v54, v62, v63
	v_cvt_pk_bf16_f32 v55, v64, v65
	v_mul_f32_e32 v56, v71, v71
	v_mul_f32_e32 v57, v75, v75
	v_pk_fma_f32 v[68:69], v[46:47], v[84:85], v[68:69]
	global_store_dwordx2 v[92:93], v[54:55], off offset:1024
	v_lshlrev_b32_e32 v90, 16, v54
	v_and_b32_e32 v91, 0xffff0000, v54
	v_lshlrev_b32_e32 v94, 16, v55
	v_and_b32_e32 v95, 0xffff0000, v55
	v_cvt_pk_bf16_f32 v54, v66, v67
	v_cvt_pk_bf16_f32 v55, v68, v69
	v_fmac_f32_e32 v56, v70, v70
	v_fmac_f32_e32 v57, v74, v74
	v_mul_f32_e32 v58, v79, v79
	v_mul_f32_e32 v59, v83, v83
	global_store_dwordx2 v[92:93], v[54:55], off offset:1536
	v_lshlrev_b32_e32 v92, 16, v54
	v_and_b32_e32 v93, 0xffff0000, v54
	v_lshlrev_b32_e32 v112, 16, v55
	v_and_b32_e32 v113, 0xffff0000, v55
	v_add_f32_e32 v54, v56, v57
	v_fmac_f32_e32 v58, v78, v78
	v_fmac_f32_e32 v59, v82, v82
	v_mul_f32_e32 v55, v91, v91
	v_mul_f32_e32 v56, v95, v95
	v_add_f32_e32 v57, v58, v59
	v_fmac_f32_e32 v55, v90, v90
	v_fmac_f32_e32 v56, v94, v94
	v_mul_f32_e32 v58, v93, v93
	v_mul_f32_e32 v59, v113, v113
	v_add_f32_e32 v54, v54, v57
	v_add_f32_e32 v55, v55, v56
	v_fmac_f32_e32 v58, v92, v92
	v_fmac_f32_e32 v59, v112, v112
	v_add_f32_e32 v54, v54, v55
	v_add_f32_e32 v55, v58, v59
	v_add_f32_e32 v54, v54, v55
	s_waitcnt vmcnt(10)
; #define GAS __attribute__((address_space(1)))
; __device__ __forceinline__ float wave_sum(float v) { return xrow_sum(row16_sum(v)); }
; __device__ __forceinline__ unsigned pk_bf16(float lo, float hi) { return pg8::cvt_pk_bf16(lo, hi); }
; __device__ __forceinline__ void xcd_barrier(const XcdBarrier& b) {
;     asm volatile("s_waitcnt vmcnt(0)" ::: "memory");
;     __syncthreads();
;     if (threadIdx.x == 0) {
;         unsigned* bar = b.bar;
;         __builtin_amdgcn_s_waitcnt(0);
;         unsigned nloc = b.st[0], nx = b.st[1];
;         if (nloc == 0u) { xcd_barrier_complete(bar, b.x, nloc, nx); b.st[0] = nloc; b.st[1] = nx; }
; template <bool HAS_F, bool HAS_H, bool XIN_B = false, bool XOUT_B = false> ...
;     ...
;         if (HAS_H) {
;             float ss = 0.f;
; #pragma unroll
;             for (int j = 0; j < 4; ++j) ss += (x[j].x * x[j].x + x[j].y * x[j].y) + (x[j].z * x[j].z + x[j].w * x[j].w);
;             const float rstd = 1.0f / sqrtf(wave_sum(ss) * (1.0f / DM) + RMS_EPS);
; #pragma unroll
;             for (int j = 0; j < 4; ++j) { const f32x4 h = x[j] * rstd * A[j] + Sh[j]; u32x2 w; w.x = pk_bf16(h.x, h.y); w.y = pk_bf16(h.z, h.w);
;                 *(GAS u32x2*)(H + (size_t)row * DM + 256 * j + 4 * lane) = w; }
	v_lshlrev_b32_e32 v61, 16, v98
	v_lshlrev_b32_e32 v63, 16, v99
	v_add_f32_dpp v54, v54, v54 quad_perm:[1,0,3,2] row_mask:0xf bank_mask:0xf bound_ctrl:1
	v_and_b32_e32 v64, 0xffff0000, v99
	s_waitcnt vmcnt(9)
	v_lshlrev_b32_e32 v67, 16, v101
	v_add_f32_dpp v54, v54, v54 quad_perm:[2,3,0,1] row_mask:0xf bank_mask:0xf bound_ctrl:1
	v_and_b32_e32 v60, 0xffff0000, v97
	v_and_b32_e32 v62, 0xffff0000, v98
	v_add_f32_dpp v54, v54, v54 row_half_mirror row_mask:0xf bank_mask:0xf bound_ctrl:1
	v_lshlrev_b32_e32 v65, 16, v100
	v_and_b32_e32 v66, 0xffff0000, v100
	v_add_f32_dpp v54, v54, v54 row_mirror row_mask:0xf bank_mask:0xf bound_ctrl:1
	v_mov_b32_e32 v55, v54
	s_nop 1
	v_permlane16_swap_b32_e32 v54, v55
	v_add_f32_e32 v54, v54, v55
	v_mov_b32_e32 v55, v54
	s_nop 1
	v_permlane32_swap_b32_e32 v54, v55
	v_add_f32_e32 v54, v54, v55
	v_fmamk_f32 v54, v54, 0x3a800000, v88
	v_mul_f32_e32 v55, 0x4f800000, v54
	v_cmp_gt_f32_e32 vcc, s12, v54
	v_and_b32_e32 v68, 0xffff0000, v101
	s_waitcnt vmcnt(8)
	v_lshlrev_b32_e32 v69, 16, v102
	v_cndmask_b32_e32 v54, v54, v55, vcc
	v_sqrt_f32_e32 v55, v54
	v_and_b32_e32 v98, 0xffff0000, v103
	s_waitcnt vmcnt(4)
	v_mov_b64_e32 v[84:85], v[110:111]
	v_mov_b64_e32 v[80:81], v[108:109]
	v_add_u32_e32 v56, -1, v55
	v_add_u32_e32 v57, 1, v55
	v_fma_f32 v58, -v56, v55, v54
	v_fma_f32 v59, -v57, v55, v54
	v_cmp_ge_f32_e64 s[6:7], 0, v58
	v_and_b32_e32 v58, 0xffff0000, v96
	v_mov_b64_e32 v[76:77], v[106:107]
	v_cndmask_b32_e64 v55, v55, v56, s[6:7]
	v_cmp_lt_f32_e64 s[6:7], 0, v59
	v_lshlrev_b32_e32 v59, 16, v97
	v_lshlrev_b32_e32 v97, 16, v103
	v_cndmask_b32_e64 v55, v55, v57, s[6:7]
	v_mul_f32_e32 v56, 0x37800000, v55
	v_cndmask_b32_e32 v55, v55, v56, vcc
	v_cmp_class_f32_e32 vcc, v54, v89
	v_lshlrev_b32_e32 v57, 16, v96
	v_and_b32_e32 v96, 0xffff0000, v102
	v_cndmask_b32_e32 v114, v55, v54, vcc
	v_div_scale_f32 v54, s[6:7], v114, v114, 1.0
	v_rcp_f32_e32 v115, v54
	v_div_scale_f32 v55, vcc, 1.0, v114, 1.0
	v_mov_b64_e32 v[72:73], v[104:105]
	v_fma_f32 v56, -v54, v115, 1.0
	v_fmac_f32_e32 v115, v56, v115
	v_mul_f32_e32 v116, v55, v115
	v_fma_f32 v56, -v54, v116, v55
	v_fmac_f32_e32 v116, v56, v115
	v_fma_f32 v99, -v54, v116, v55
	v_mov_b32_e32 v55, v58
	v_mov_b32_e32 v58, v61
	v_mov_b32_e32 v61, v64
	v_mov_b32_e32 v64, v67
	v_mov_b32_e32 v67, v96
	v_div_fmas_f32 v96, v99, v115, v116
	v_div_fixup_f32 v96, v96, v114, 1.0
	v_pk_mul_f32 v[70:71], v[70:71], v[96:97] op_sel_hi:[1,0]
	v_pk_mul_f32 v[74:75], v[74:75], v[96:97] op_sel_hi:[1,0]
	v_pk_fma_f32 v[70:71], v[28:29], v[70:71], v[0:1]
	v_pk_mul_f32 v[78:79], v[78:79], v[96:97] op_sel_hi:[1,0]
	v_pk_mul_f32 v[82:83], v[82:83], v[96:97] op_sel_hi:[1,0]
	v_pk_fma_f32 v[74:75], v[26:27], v[74:75], v[2:3]
	v_cvt_pk_bf16_f32 v70, v70, v71
	v_pk_mul_f32 v[90:91], v[90:91], v[96:97] op_sel_hi:[1,0]
	v_cvt_pk_bf16_f32 v71, v74, v75
	v_pk_mul_f32 v[94:95], v[94:95], v[96:97] op_sel_hi:[1,0]
	v_pk_fma_f32 v[82:83], v[30:31], v[82:83], v[10:11]
	v_pk_fma_f32 v[78:79], v[32:33], v[78:79], v[8:9]
	global_store_dwordx2 v[86:87], v[70:71], off
	v_cvt_pk_bf16_f32 v70, v78, v79
	v_cvt_pk_bf16_f32 v71, v82, v83
	v_mov_b32_e32 v54, v57
	v_mov_b32_e32 v56, v59
	v_mov_b32_e32 v57, v60
	v_mov_b32_e32 v59, v62
	v_mov_b32_e32 v60, v63
	v_mov_b32_e32 v62, v65
	v_mov_b32_e32 v63, v66
	v_mov_b32_e32 v65, v68
	v_mov_b32_e32 v66, v69
	v_mov_b32_e32 v68, v97
	v_mov_b32_e32 v69, v98
	v_pk_mul_f32 v[92:93], v[92:93], v[96:97] op_sel_hi:[1,0]
	v_pk_mul_f32 v[96:97], v[112:113], v[96:97] op_sel_hi:[1,0]
	v_pk_fma_f32 v[94:95], v[34:35], v[94:95], v[6:7]
	v_pk_fma_f32 v[90:91], v[36:37], v[90:91], v[4:5]
	global_store_dwordx2 v[86:87], v[70:71], off offset:512
	v_cvt_pk_bf16_f32 v70, v90, v91
	v_cvt_pk_bf16_f32 v71, v94, v95
	s_mov_b64 vcc, s[4:5]
	v_pk_fma_f32 v[96:97], v[38:39], v[96:97], v[14:15]
	v_pk_fma_f32 v[92:93], v[40:41], v[92:93], v[12:13]
	global_store_dwordx2 v[86:87], v[70:71], off offset:1024
	v_cvt_pk_bf16_f32 v70, v92, v93
	v_cvt_pk_bf16_f32 v71, v96, v97
	global_store_dwordx2 v[86:87], v[70:71], off offset:1536
	s_cbranch_vccnz .LBB0_637
	s_waitcnt vmcnt(0)
	s_barrier
	s_and_saveexec_b64 s[4:5], s[26:27]
	s_xor_b64 s[52:53], exec, s[4:5]
	s_cbranch_execz .LBB0_683
	s_add_i32 s3, 0, 0x20020
	v_mov_b32_e32 v0, s3
	s_waitcnt vmcnt(0) expcnt(0) lgkmcnt(0)
	ds_read_b32 v2, v0
	s_add_i32 s3, 0, 0x20024
	v_mov_b32_e32 v0, s3
	ds_read_b32 v0, v0
	s_waitcnt lgkmcnt(1)
	v_cmp_ne_u32_e32 vcc, 0, v2
	s_cbranch_vccnz .LBB0_653
	s_add_u32 s4, s40, 0x80200
	s_addc_u32 s5, s41, 0
	s_add_u32 s8, s40, 0x80400
	s_addc_u32 s9, s41, 0
	s_add_u32 s10, s40, 0x80500
	s_addc_u32 s11, s41, 0
	s_add_u32 s12, s40, 0x80600
	s_addc_u32 s13, s41, 0
	s_add_u32 s14, s40, 0x80700
	s_addc_u32 s15, s41, 0
	s_add_u32 s16, s40, 0x80800
	s_addc_u32 s17, s41, 0
	s_add_u32 s18, s40, 0x80900
	s_addc_u32 s19, s41, 0
	s_add_u32 s20, s40, 0x80a00
	s_addc_u32 s21, s41, 0
	s_add_u32 s22, s40, 0x80b00
	s_addc_u32 s23, s41, 0
	s_add_u32 s28, s40, 0x80c00
	s_addc_u32 s29, s41, 0
	s_add_u32 s30, s40, 0x80d00
	s_addc_u32 s31, s41, 0
	s_add_u32 s34, s40, 0x80e00
	s_addc_u32 s35, s41, 0
	s_add_u32 s36, s40, 0x80f00
	s_addc_u32 s37, s41, 0
	s_add_u32 s48, s40, 0x81000
	s_addc_u32 s49, s41, 0
	s_add_u32 s54, s40, 0x81100
	s_addc_u32 s55, s41, 0
	s_add_u32 s56, s40, 0x81200
	s_addc_u32 s57, s41, 0
	s_add_u32 s58, s40, 0x81300
	s_mul_i32 s24, s43, s92
	s_addc_u32 s59, s41, 0
	s_mul_i32 s24, s24, s42
	s_mov_b32 s25, 1
	s_mov_b64 s[6:7], 0
	s_waitcnt lgkmcnt(0)
	v_mov_b64_e32 v[0:1], s[8:9]
	v_mov_b64_e32 v[2:3], s[10:11]
	v_mov_b64_e32 v[4:5], s[12:13]
	v_mov_b64_e32 v[6:7], s[14:15]
	v_mov_b64_e32 v[8:9], s[16:17]
	v_mov_b64_e32 v[10:11], s[18:19]
	v_mov_b64_e32 v[12:13], s[20:21]
	v_mov_b64_e32 v[14:15], s[22:23]
	v_mov_b64_e32 v[16:17], s[28:29]
	v_mov_b64_e32 v[18:19], s[30:31]
	v_mov_b64_e32 v[20:21], s[34:35]
	v_mov_b64_e32 v[22:23], s[36:37]
	v_mov_b64_e32 v[24:25], s[48:49]
	v_mov_b64_e32 v[26:27], s[54:55]
	v_mov_b64_e32 v[28:29], s[56:57]
	v_mov_b64_e32 v[30:31], s[58:59]
	s_branch .LBB0_643

; #define GAS __attribute__((address_space(1)))
; __device__ __forceinline__ float wave_sum(float v) { return xrow_sum(row16_sum(v)); }
; __device__ __forceinline__ unsigned pk_bf16(float lo, float hi) { return pg8::cvt_pk_bf16(lo, hi); }
; template <bool HAS_F, bool HAS_H, bool XIN_B = false, bool XOUT_B = false> ...
;     ...
;     for (int row = row_lo; row < row_lo + RPW; ++row) {
;         f32x4 x[4]; u32x2 fwv[4];
; #pragma unroll
;         for (int j = 0; j < 4; ++j) { x[j] = xn[j]; if (HAS_F) fwv[j] = fn[j]; }
;         { const int rn = (row + 1 < row_lo + RPW) ? row + 1 : row;
; #pragma unroll
;           for (int j = 0; j < 4; ++j) { RP_LDX(xn[j], rn, j); if (HAS_F) fn[j] = __builtin_nontemporal_load((const GAS u32x2*)(Fb + (size_t)rn * DM + 256 * j + 4 * lane)); } }
;         if (HAS_F) {
;             f32x4 f[4]; float ss = 0.f;
; #pragma unroll
;             for (int j = 0; j < 4; ++j) { const u32x2 fw = fwv[j];
;                 f[j] = (f32x4){__uint_as_float(fw.x << 16), __uint_as_float(fw.x & 0xffff0000u), __uint_as_float(fw.y << 16), __uint_as_float(fw.y & 0xffff0000u)}; ss += (f[j].x * f[j].x + f[j].y * f[j].y) + (f[j].z * f[j].z + f[j].w * f[j].w); }
;             const float rstd = 1.0f / sqrtf(wave_sum(ss) * (1.0f / DM) + RMS_EPS);
; #pragma unroll
;             for (int j = 0; j < 4; ++j) { x[j] = x[j] + f[j] * rstd * Cg[j];
;                 if (XOUT_B) { u32x2 w; w.x = pk_bf16(x[j].x, x[j].y); w.y = pk_bf16(x[j].z, x[j].w); *(GAS u32x2*)(xoutb + (size_t)row * DM + 256 * j + 4 * lane) = w;
;                     x[j] = (f32x4){__uint_as_float(w.x << 16), __uint_as_float(w.x & 0xffff0000u), __uint_as_float(w.y << 16), __uint_as_float(w.y & 0xffff0000u)}; }
;                 else __builtin_nontemporal_store(x[j], (GAS f32x4*)(xout + (size_t)row * DM + 256 * j + 4 * lane)); }
;         }
.LBB0_810:
	s_add_i32 s3, s44, 1
	v_lshlrev_b32_e32 v48, 16, v44
	v_and_b32_e32 v49, 0xffff0000, v44
	v_lshlrev_b32_e32 v44, 16, v45
	v_and_b32_e32 v45, 0xffff0000, v45
	v_lshlrev_b32_e32 v50, 16, v42
	v_and_b32_e32 v51, 0xffff0000, v42
	v_lshlrev_b32_e32 v42, 16, v43
	v_and_b32_e32 v43, 0xffff0000, v43
	s_cmp_lt_i32 s44, s70
	v_lshlrev_b32_e32 v52, 16, v40
	v_and_b32_e32 v53, 0xffff0000, v40
	v_lshlrev_b32_e32 v40, 16, v41
	v_and_b32_e32 v41, 0xffff0000, v41
	v_mul_f32_e32 v56, v49, v49
	v_mul_f32_e32 v57, v45, v45
	v_mul_f32_e32 v58, v51, v51
	v_mul_f32_e32 v59, v43, v43
	s_cselect_b64 s[0:1], -1, 0
	v_lshlrev_b32_e32 v54, 16, v38
	v_and_b32_e32 v55, 0xffff0000, v38
	v_lshlrev_b32_e32 v38, 16, v39
	v_and_b32_e32 v39, 0xffff0000, v39
	v_mul_f32_e32 v60, v53, v53
	v_mul_f32_e32 v61, v41, v41
	v_fmac_f32_e32 v56, v48, v48
	v_fmac_f32_e32 v57, v44, v44
	v_fmac_f32_e32 v58, v50, v50
	v_fmac_f32_e32 v59, v42, v42
	s_and_b64 s[0:1], s[0:1], exec
	v_mul_f32_e32 v62, v55, v55
	v_mul_f32_e32 v63, v39, v39
	v_fmac_f32_e32 v60, v52, v52
	v_fmac_f32_e32 v61, v40, v40
	v_add_f32_e32 v56, v56, v57
	v_add_f32_e32 v57, v58, v59
	s_cselect_b32 s2, s3, s44
	v_fmac_f32_e32 v62, v54, v54
	v_fmac_f32_e32 v63, v38, v38
	v_add_f32_e32 v58, v60, v61
	v_add_f32_e32 v56, v57, v56
	s_mov_b32 s44, s3
	s_ashr_i32 s3, s2, 31
	v_add_f32_e32 v59, v62, v63
	v_add_f32_e32 v56, v58, v56
	s_lshl_b64 s[2:3], s[2:3], 11
	v_add_f32_e32 v60, v59, v56
	v_lshl_add_u64 v[56:57], v[0:1], 0, s[2:3]
	v_lshl_add_u64 v[58:59], v[2:3], 0, s[2:3]
	v_add_f32_dpp v76, v60, v60 quad_perm:[1,0,3,2] row_mask:0xf bank_mask:0xf bound_ctrl:1
	s_mov_b64 exec, s[0:1]
	global_load_dwordx2 v[60:61], v[56:57], off nt
	global_load_dwordx2 v[62:63], v[56:57], off offset:512 nt
	global_load_dwordx2 v[64:65], v[56:57], off offset:1024 nt
	global_load_dwordx2 v[66:67], v[56:57], off offset:1536 nt
	global_load_dwordx2 v[68:69], v[58:59], off nt
	global_load_dwordx2 v[70:71], v[58:59], off offset:512 nt
	global_load_dwordx2 v[72:73], v[58:59], off offset:1024 nt
	global_load_dwordx2 v[74:75], v[58:59], off offset:1536 nt
	s_mov_b64 exec, -1
	s_nop 4
	v_add_f32_dpp v56, v76, v76 quad_perm:[2,3,0,1] row_mask:0xf bank_mask:0xf bound_ctrl:1
	s_nop 1
	v_add_f32_dpp v56, v56, v56 row_half_mirror row_mask:0xf bank_mask:0xf bound_ctrl:1
	s_nop 1
	v_add_f32_dpp v56, v56, v56 row_mirror row_mask:0xf bank_mask:0xf bound_ctrl:1
	v_mov_b32_e32 v57, v56
	s_nop 1
	v_permlane16_swap_b32_e32 v56, v57
	v_add_f32_e32 v56, v56, v57
	v_mov_b32_e32 v57, v56
	s_nop 1
	v_permlane32_swap_b32_e32 v56, v57
	v_add_f32_e32 v56, v56, v57
	v_fmamk_f32 v56, v56, 0x3a800000, v46
	v_mul_f32_e32 v57, 0x4f800000, v56
	v_cmp_gt_f32_e32 vcc, s6, v56
	s_nop 1
	v_cndmask_b32_e32 v56, v56, v57, vcc
	v_sqrt_f32_e32 v57, v56
	s_nop 0
	v_add_u32_e32 v58, -1, v57
	v_add_u32_e32 v59, 1, v57
	v_fma_f32 v76, -v58, v57, v56
	v_fma_f32 v77, -v59, v57, v56
	v_cmp_ge_f32_e64 s[2:3], 0, v76
	s_nop 1
	v_cndmask_b32_e64 v57, v57, v58, s[2:3]
	v_cmp_lt_f32_e64 s[2:3], 0, v77
	s_nop 1
	v_cndmask_b32_e64 v57, v57, v59, s[2:3]
	v_mul_f32_e32 v58, 0x37800000, v57
	v_cndmask_b32_e32 v57, v57, v58, vcc
	v_cmp_class_f32_e32 vcc, v56, v47
	s_nop 1
	v_cndmask_b32_e32 v56, v57, v56, vcc
	v_div_scale_f32 v57, s[2:3], v56, v56, 1.0
	v_rcp_f32_e32 v59, v57
	v_div_scale_f32 v58, vcc, 1.0, v56, 1.0
	v_fma_f32 v76, -v57, v59, 1.0
	v_fmac_f32_e32 v59, v76, v59
	v_mul_f32_e32 v76, v58, v59
	v_fma_f32 v77, -v57, v76, v58
	v_fmac_f32_e32 v76, v77, v59
	v_fma_f32 v57, -v57, v76, v58
	v_div_fmas_f32 v57, v57, v59, v76
	v_div_fixup_f32 v56, v57, v56, 1.0
	v_pk_mul_f32 v[48:49], v[48:49], v[56:57] op_sel_hi:[1,0]
	v_pk_mul_f32 v[44:45], v[44:45], v[56:57] op_sel_hi:[1,0]
	v_pk_mul_f32 v[50:51], v[50:51], v[56:57] op_sel_hi:[1,0]
	v_pk_mul_f32 v[42:43], v[42:43], v[56:57] op_sel_hi:[1,0]
	v_pk_mul_f32 v[52:53], v[52:53], v[56:57] op_sel_hi:[1,0]
	v_pk_mul_f32 v[40:41], v[40:41], v[56:57] op_sel_hi:[1,0]
	v_pk_mul_f32 v[54:55], v[54:55], v[56:57] op_sel_hi:[1,0]
	v_pk_mul_f32 v[38:39], v[38:39], v[56:57] op_sel_hi:[1,0]
	v_pk_fma_f32 v[24:25], v[6:7], v[44:45], v[24:25]
	v_pk_fma_f32 v[22:23], v[8:9], v[48:49], v[22:23]
	v_pk_fma_f32 v[28:29], v[10:11], v[42:43], v[28:29]
	v_pk_fma_f32 v[26:27], v[12:13], v[50:51], v[26:27]
	v_pk_fma_f32 v[32:33], v[14:15], v[40:41], v[32:33]
	v_pk_fma_f32 v[30:31], v[16:17], v[52:53], v[30:31]
	v_pk_fma_f32 v[36:37], v[18:19], v[38:39], v[36:37]
	v_pk_fma_f32 v[34:35], v[20:21], v[54:55], v[34:35]
	global_store_dwordx4 v[4:5], v[22:25], off offset:-3072 nt
	global_store_dwordx4 v[4:5], v[26:29], off offset:-2048 nt
	global_store_dwordx4 v[4:5], v[30:33], off offset:-1024 nt
	global_store_dwordx4 v[4:5], v[34:37], off nt
	v_lshl_add_u64 v[4:5], v[4:5], 0, s[4:5]
	s_waitcnt vmcnt(11)
	v_lshlrev_b32_e32 v22, 16, v60
	v_and_b32_e32 v23, 0xffff0000, v60
	v_lshlrev_b32_e32 v24, 16, v61
	v_and_b32_e32 v25, 0xffff0000, v61
	s_waitcnt vmcnt(10)
	v_lshlrev_b32_e32 v26, 16, v62
	v_and_b32_e32 v27, 0xffff0000, v62
	v_lshlrev_b32_e32 v28, 16, v63
	v_and_b32_e32 v29, 0xffff0000, v63
	s_waitcnt vmcnt(9)
	v_lshlrev_b32_e32 v30, 16, v64
	v_and_b32_e32 v31, 0xffff0000, v64
	v_lshlrev_b32_e32 v32, 16, v65
	v_and_b32_e32 v33, 0xffff0000, v65
	s_waitcnt vmcnt(8)
	v_lshlrev_b32_e32 v34, 16, v66
	v_and_b32_e32 v35, 0xffff0000, v66
	v_lshlrev_b32_e32 v36, 16, v67
	v_and_b32_e32 v37, 0xffff0000, v67
	s_waitcnt vmcnt(4)
	v_mov_b64_e32 v[38:39], v[74:75]
	v_mov_b64_e32 v[40:41], v[72:73]
	v_mov_b64_e32 v[42:43], v[70:71]
	v_mov_b64_e32 v[44:45], v[68:69]
	s_mov_b64 vcc, s[0:1]
	s_cbranch_vccnz .LBB0_810
	s_endpgm

; __global__ void __launch_bounds__(512) fwd_megakernel(Args args) {
	.amdhsa_kernel _Z14fwd_megakernel4Args
		.amdhsa_group_segment_fixed_size 0
		.amdhsa_private_segment_fixed_size 0
		.amdhsa_kernarg_size 464
		.amdhsa_user_sgpr_count 2
		.amdhsa_user_sgpr_dispatch_ptr 0
		.amdhsa_user_sgpr_queue_ptr 0
		.amdhsa_user_sgpr_kernarg_segment_ptr 1
		.amdhsa_user_sgpr_dispatch_id 0
		.amdhsa_user_sgpr_kernarg_preload_length 0
		.amdhsa_user_sgpr_kernarg_preload_offset 0
		.amdhsa_user_sgpr_private_segment_size 0
		.amdhsa_uses_dynamic_stack 0
		.amdhsa_enable_private_segment 0
		.amdhsa_system_sgpr_workgroup_id_x 1
		.amdhsa_system_sgpr_workgroup_id_y 0
		.amdhsa_system_sgpr_workgroup_id_z 0
		.amdhsa_system_sgpr_workgroup_info 0
		.amdhsa_system_vgpr_workitem_id 2
		.amdhsa_next_free_vgpr 240
		.amdhsa_next_free_sgpr 102
		.amdhsa_accum_offset 240
		.amdhsa_reserve_vcc 1
		.amdhsa_float_round_mode_32 0
		.amdhsa_float_round_mode_16_64 0
		.amdhsa_float_denorm_mode_32 3
		.amdhsa_float_denorm_mode_16_64 3
		.amdhsa_dx10_clamp 1
		.amdhsa_ieee_mode 1
		.amdhsa_fp16_overflow 0
		.amdhsa_tg_split 0
		.amdhsa_exception_fp_ieee_invalid_op 0
		.amdhsa_exception_fp_denorm_src 0
		.amdhsa_exception_fp_ieee_div_zero 0
		.amdhsa_exception_fp_ieee_overflow 0
		.amdhsa_exception_fp_ieee_underflow 0
		.amdhsa_exception_fp_ieee_inexact 0
		.amdhsa_exception_int_div_zero 0
	.end_amdhsa_kernel

; __global__ void __launch_bounds__(512) fwd_megakernel(Args args) {
amdhsa.kernels:
  - .agpr_count:     0
    .args:
      - .offset:         0
        .size:           208
        .value_kind:     by_value
      - .offset:         208
        .size:           4
        .value_kind:     hidden_block_count_x
      - .offset:         212
        .size:           4
        .value_kind:     hidden_block_count_y
      - .offset:         216
        .size:           4
        .value_kind:     hidden_block_count_z
      - .offset:         220
        .size:           2
        .value_kind:     hidden_group_size_x
      - .offset:         222
        .size:           2
        .value_kind:     hidden_group_size_y
      - .offset:         224
        .size:           2
        .value_kind:     hidden_group_size_z
      - .offset:         226
        .size:           2
        .value_kind:     hidden_remainder_x
      - .offset:         228
        .size:           2
        .value_kind:     hidden_remainder_y
      - .offset:         230
        .size:           2
        .value_kind:     hidden_remainder_z
      - .offset:         248
        .size:           8
        .value_kind:     hidden_global_offset_x
      - .offset:         256
        .size:           8
        .value_kind:     hidden_global_offset_y
      - .offset:         264
        .size:           8
        .value_kind:     hidden_global_offset_z
      - .offset:         272
        .size:           2
        .value_kind:     hidden_grid_dims
      - .offset:         296
        .size:           8
        .value_kind:     hidden_multigrid_sync_arg
      - .offset:         328
        .size:           4
        .value_kind:     hidden_dynamic_lds_size
    .group_segment_fixed_size: 0
    .kernarg_segment_align: 8
    .kernarg_segment_size: 464
    .language:       OpenCL C
    .language_version:
      - 2
      - 0
    .max_flat_workgroup_size: 512
    .name:           _Z14fwd_megakernel4Args
    .private_segment_fixed_size: 0
    .sgpr_count:     108
    .sgpr_spill_count: 4
    .symbol:         _Z14fwd_megakernel4Args.kd
    .uniform_work_group_size: 1
    .uses_dynamic_stack: false
    .vgpr_count:     240
    .vgpr_spill_count: 0
    .wavefront_size: 64
